# v20 + attention tile loops laid out with fall-through between the unrolled copies (masked-tile blocks out of line; one taken branch per 3 tiles instead of 3)
# speedup vs baseline: 1.0054x; 1.0054x over previous
; #define ATT_ISSUE_K(jt, stage) do { _Pragma("unroll") for (int i_ = 0; i_ < 3; ++i_) ATT_DMA(kg + (size_t)(jt) * KTILE + kgo[i_], KRING + (stage) * KTILE + (wave * 3 + i_) * 1024); } while (0)
; #define ATT_ISSUE_V(jt, stage) do { _Pragma("unroll") for (int i_ = 0; i_ < 2; ++i_) ATT_DMA(vg + (size_t)(jt) * 128 + vgo[i_], VRING + (stage) * VTILE + (wave * 2 + i_) * 1024); } while (0)
; __device__ __forceinline__ void attn_unit(LAS unsigned char* lds, const bf16_t* Qg, const bf16_t* Kg, const bf16_t* Vtg, bf16_t* Og, int bh, int qb, int tid_, int wave, int lane_) {
;     ...
;     const int rg = wave & 3, kh = wave >> 2, r = lane & 31, hi = lane >> 5;
;     const int b = bh >> 2, h = bh & 3;
;     const int nt = 2 * (qb + 1);
;     const float NEG = -1e30f;
;     bf16x8 qf[12];
;     { const bf16_t* qp = Qg + ((size_t)bh * SEQ + 128 * qb + 32 * rg + r) * QKD + 8 * hi;
; #pragma unroll
;       for (int kk = 0; kk < 12; ++kk) qf[kk] = *(const bf16x8*)(qp + 16 * kk); }
;     const unsigned char* kg = (const unsigned char*)(Kg + (size_t)bh * SEQ * QKD);
;     const unsigned char* vg = (const unsigned char*)(Vtg + (size_t)bh * VD * SEQ);
;     unsigned kgo[3], vgo[2];
; #pragma unroll
;     for (int i = 0; i < 3; ++i) { const int a = (wave * 3 + i) * 1024 + lane * 16, row = a / 384, cp = (a % 384) >> 4, cl = (cp & ~7) | ((cp ^ (row >> 1)) & 7); kgo[i] = (unsigned)(row * 384 + cl * 16); }
; #pragma unroll
;     for (int i = 0; i < 2; ++i) { const int a = (wave * 2 + i) * 1024 + lane * 16, row = a >> 7, cp = (a & 127) >> 4, cl = (cp ^ (row >> 1)) & 7; vgo[i] = (unsigned)(row * (SEQ * 2) + cl * 16); }
;     const int sw = (r >> 1) & 7;
;     unsigned kro[4], vro[2];
; #pragma unroll
;     for (int q = 0; q < 4; ++q) kro[q] = (unsigned)((32 * kh + r) * 384 + (((2 * q + hi) ^ sw) * 16));
; #pragma unroll
;     for (int s = 0; s < 2; ++s) vro[s] = (unsigned)(VRING + r * 128 + (((4 * kh + 2 * s + hi) ^ sw) * 16));
;     f32x16 o[4]; float mrun = NEG, lrun = 0.f;
; #pragma unroll
;     for (int dt = 0; dt < 4; ++dt)
; #pragma unroll
;         for (int i = 0; i < 16; ++i) o[dt][i] = 0.f;
;     ATT_ISSUE_K(0, 0); ATT_ISSUE_V(0, 0); ATT_ISSUE_K(1, 1);
;     ATT_ISSUE_K((2 < nt) ? 2 : nt - 1, 2); ATT_ISSUE_V(1, 1);
;     asm volatile("s_waitcnt vmcnt(5)" ::: "memory"); __builtin_amdgcn_s_barrier(); asm volatile("" ::: "memory");
.LBB0_475:
	s_ashr_i32 s40, s72, 3
	s_sub_i32 s0, 63, s40
	s_and_b32 s73, s72, 7
	s_lshl_b32 s66, s0, 7
	s_mov_b64 s[8:9], s[88:89]
	s_lshl_b32 s44, s0, 1
	s_lshl_b32 s41, s73, 13
	s_ashr_i32 s88, s66, 31
	v_mov_b32_e32 v4, v254
	s_add_u32 s0, s41, s66
	s_addc_u32 s4, 0, s88
	v_and_b32_e32 v180, 31, v4
	s_or_b32 s0, s0, s97
	v_or_b32_e32 v0, s0, v180
	v_bfe_u32 v24, v4, 5, 1
	v_mad_u64_u32 v[0:1], s[0:1], v0, s61, v[178:179]
	v_mad_i32_i24 v1, s4, v195, v1
	v_lshlrev_b32_e32 v176, 4, v24
	v_and_b32_e32 v181, 63, v4
	v_lshl_add_u64 v[0:1], v[0:1], 0, v[176:177]
	global_load_dwordx4 v[96:99], v[0:1], off
	global_load_dwordx4 v[100:103], v[0:1], off offset:32
	global_load_dwordx4 v[104:107], v[0:1], off offset:64
	global_load_dwordx4 v[108:111], v[0:1], off offset:96
	global_load_dwordx4 v[112:115], v[0:1], off offset:128
	global_load_dwordx4 v[116:119], v[0:1], off offset:160
	global_load_dwordx4 v[120:123], v[0:1], off offset:192
	global_load_dwordx4 v[124:127], v[0:1], off offset:224
	global_load_dwordx4 v[128:131], v[0:1], off offset:256
	global_load_dwordx4 v[132:135], v[0:1], off offset:288
	global_load_dwordx4 v[136:139], v[0:1], off offset:320
	global_load_dwordx4 v[140:143], v[0:1], off offset:352
	v_lshlrev_b32_e32 v0, 4, v181
	v_or_b32_e32 v1, s59, v0
	v_mul_hi_i32 v2, v1, s42
	v_lshrrev_b32_e32 v3, 31, v2
	v_ashrrev_i32_e32 v2, 6, v2
	v_add_u32_e32 v2, v2, v3
	v_mul_i32_i24_e32 v3, 0x180, v2
	v_lshlrev_b32_e32 v2, 3, v2
	v_sub_u32_e32 v1, v1, v3
	v_and_b32_e32 v2, 0x70, v2
	v_xad_u32 v176, v2, v1, v3
	v_or_b32_e32 v1, s60, v0
	v_mul_hi_i32 v2, v1, s42
	v_lshrrev_b32_e32 v3, 31, v2
	v_ashrrev_i32_e32 v2, 6, v2
	v_add_u32_e32 v2, v2, v3
	v_mul_i32_i24_e32 v3, 0x180, v2
	v_lshlrev_b32_e32 v2, 3, v2
	v_sub_u32_e32 v1, v1, v3
	v_and_b32_e32 v2, 0x70, v2
	v_xad_u32 v182, v2, v1, v3
	v_or_b32_e32 v1, s67, v0
	v_mul_hi_i32 v2, v1, s42
	v_lshrrev_b32_e32 v3, 31, v2
	v_ashrrev_i32_e32 v2, 6, v2
	v_add_u32_e32 v2, v2, v3
	v_mul_i32_i24_e32 v3, 0x180, v2
	v_lshlrev_b32_e32 v2, 3, v2
	s_mul_i32 s0, s73, 0x300000
	s_lshl_b32 s1, s73, 21
	v_sub_u32_e32 v1, v1, v3
	v_and_b32_e32 v2, 0x70, v2
	v_readlane_b32 s4, v255, 32
	v_xad_u32 v184, v2, v1, v3
	v_readlane_b32 s5, v255, 33
	s_add_u32 s92, s4, s0
	v_or_b32_e32 v0, s68, v0
	v_lshlrev_b32_e32 v2, 4, v4
	v_and_b32_e32 v3, 48, v4
	s_mov_b32 m0, s71
	s_addc_u32 s93, s5, 0
	v_lshlrev_b32_e32 v1, 7, v0
	v_bitop3_b32 v2, v2, v3, s86 bitop3:0x6c
	v_or_b32_e32 v0, 0x400, v0
	v_and_or_b32 v186, v1, s62, v2
	v_lshrrev_b32_e32 v1, 8, v0
	s_add_i32 s89, s44, 2
	global_load_lds_dwordx4 v176, s[92:93]
	s_mov_b32 m0, s91
	v_readlane_b32 s0, v255, 52
	v_xor_b32_e32 v1, v1, v4
	v_lshlrev_b32_e32 v0, 7, v0
	global_load_lds_dwordx4 v182, s[92:93]
	s_mov_b32 m0, s74
	s_add_u32 s94, s0, s1
	v_readlane_b32 s0, v255, 53
	v_and_b32_e32 v0, 0xffffc000, v0
	v_lshlrev_b32_e32 v1, 4, v1
	global_load_lds_dwordx4 v184, s[92:93]
	s_addc_u32 s95, s0, 0
	s_mov_b32 m0, s96
	v_and_or_b32 v188, v1, s86, v0
	global_load_lds_dwordx4 v186, s[94:95]
	s_mov_b32 m0, s43
	s_add_u32 s38, s92, 0x6000
	global_load_lds_dwordx4 v188, s[94:95]
	s_addc_u32 s39, s93, 0
	s_mov_b32 m0, s75
	s_or_b32 s45, s44, 1
	global_load_lds_dwordx4 v176, s[38:39]
	s_mov_b32 m0, s90
	s_add_u32 s0, s92, 0xc000
	global_load_lds_dwordx4 v182, s[38:39]
	s_mov_b32 m0, s2
	s_addc_u32 s1, s93, 0
	global_load_lds_dwordx4 v184, s[38:39]
	s_mov_b32 m0, s85
	v_mov_b32_e32 v187, v177
	global_load_lds_dwordx4 v176, s[0:1]
	s_mov_b32 m0, s87
	v_lshl_add_u64 v[0:1], s[94:95], 0, v[186:187]
	v_mov_b32_e32 v189, v177
	global_load_lds_dwordx4 v182, s[0:1]
	s_mov_b32 m0, s3
	v_lshl_add_u64 v[2:3], s[94:95], 0, v[188:189]
	global_load_lds_dwordx4 v184, s[0:1]
	v_lshl_add_u64 v[0:1], v[0:1], 0, s[78:79]
	s_mov_b32 m0, s33
	v_or_b32_e32 v5, s70, v24
	global_load_lds_dwordx4 v[0:1], off
	v_lshl_add_u64 v[0:1], v[2:3], 0, s[78:79]
	s_mov_b32 m0, s10
	s_mov_b32 s48, s49
	global_load_lds_dwordx4 v[0:1], off
	v_lshrrev_b32_e32 v0, 1, v4
	v_or_b32_e32 v1, s69, v180
	v_bfe_u32 v4, v4, 1, 3
	v_mul_lo_u32 v1, v1, s61
	v_bitop3_b32 v0, v24, v0, 7 bitop3:0x78
	v_lshl_or_b32 v191, v0, 4, v1
	v_bitop3_b32 v0, v24, v4, 2 bitop3:0x36
	v_lshl_or_b32 v197, v0, 4, v1
	v_bitop3_b32 v0, v24, v4, 4 bitop3:0x36
	v_lshl_or_b32 v199, v0, 4, v1
	v_bitop3_b32 v0, v24, v4, 6 bitop3:0x36
	s_waitcnt vmcnt(5)
	s_barrier
; #define LAS __attribute__((address_space(3)))
; #define MFMA32(a, b, c) __builtin_amdgcn_mfma_f32_32x32x16_bf16((a), (b), (c), 0, 0, 0)
; __device__ __forceinline__ void attn_unit(LAS unsigned char* lds, const bf16_t* Qg, const bf16_t* Kg, const bf16_t* Vtg, bf16_t* Og, int bh, int qb, int tid_, int wave, int lane_) {
;     ...
;     {
; #pragma unroll
;       for (int i = 0; i < 16; ++i) sc[i] = 0.f;
; #pragma unroll
;       for (int kk = 0; kk < 12; ++kk) { const bf16x8 kf = *(const LAS bf16x8*)(lds + KRING + kro[kk & 3] + (kk >> 2) * 128); sc = MFMA32(kf, qf[kk], sc); if ((kk & 3) == 3) __builtin_amdgcn_sched_barrier(0); } }
;     asm volatile("s_waitcnt lgkmcnt(0)" ::: "memory"); __builtin_amdgcn_s_barrier(); asm volatile("" ::: "memory");
;     const float NINF = -__builtin_inff();
;     int s0 = 0, s1 = 1, s2 = 2;
;     for (int j = 0; j < nt; ++j) {
;         const int relc = 64 * (j - 2 * qb) + 32 * kh - 32 * rg;
;         const int j3 = (j + 3 < nt) ? j + 3 : nt - 1, j2 = (j + 2 < nt) ? j + 2 : nt - 1;
;         const LAS unsigned char* kb = lds + KRING + s1 * KTILE;
;         const LAS unsigned char* vb = lds + s0 * VTILE;
;         if (relc >= 0) {
;             const int thr = (relc == 0) ? r : -1;
; #pragma unroll
;             for (int i = 0; i < 16; ++i) { const int key = (i & 3) + 8 * (i >> 2) + 4 * hi; if (key > thr) sc[i] = NINF; }
;         }
	v_add_u32_e32 v25, 0, v191
	v_lshl_or_b32 v200, v0, 4, v1
	ds_read_b128 v[0:3], v25
	v_bitop3_b32 v6, v24, v4, s70 bitop3:0x36
	v_bitop3_b32 v4, v5, v4, 2 bitop3:0x36
	v_add_u32_e32 v26, 0, v197
	v_lshlrev_b32_e32 v201, 4, v6
	v_lshlrev_b32_e32 v202, 4, v4
	ds_read_b128 v[4:7], v26
	s_waitcnt lgkmcnt(0)
	v_mfma_f32_32x32x16_bf16 v[64:79], v[0:3], v[96:99], 0
	v_add_u32_e32 v27, 0, v199
	ds_read_b128 v[0:3], v27
	v_add_u32_e32 v28, 0, v200
	ds_read_b128 v[16:19], v28
	s_mov_b32 s50, s49
	s_mov_b32 s51, s49
	s_mov_b32 s52, s49
	v_mfma_f32_32x32x16_bf16 v[64:79], v[4:7], v[100:103], v[64:79]
	s_mov_b32 s53, s49
	s_mov_b32 s54, s49
	s_mov_b32 s55, s49
	s_mov_b32 s56, s49
	s_mov_b32 s57, s49
	s_mov_b32 s58, s49
	s_mov_b32 s0, s59
	s_waitcnt lgkmcnt(1)
	v_mfma_f32_32x32x16_bf16 v[64:79], v[0:3], v[104:107], v[64:79]
	s_mov_b32 s59, s49
	s_mov_b32 s1, s60
	s_mov_b32 s60, s49
	s_mov_b32 s61, s49
	s_mov_b32 s62, s49
	s_mov_b32 s63, s49
	v_mov_b64_e32 v[0:1], s[48:49]
	s_waitcnt lgkmcnt(0)
	v_mfma_f32_32x32x16_bf16 v[64:79], v[16:19], v[108:111], v[64:79]
	s_mov_b32 s84, 1
	v_mov_b32_e32 v183, v177
	v_mov_b32_e32 v185, v177
	v_mov_b64_e32 v[2:3], s[50:51]
	v_mov_b64_e32 v[4:5], s[52:53]
	v_mov_b64_e32 v[6:7], s[54:55]
	v_mov_b64_e32 v[8:9], s[56:57]
	v_mov_b64_e32 v[10:11], s[58:59]
	v_mov_b64_e32 v[12:13], s[60:61]
	v_mov_b64_e32 v[14:15], s[62:63]
	s_mov_b32 s62, 0xfffdc000
	s_movk_i32 s61, 0x180
	s_mov_b32 s60, s1
	s_mov_b32 s59, s0
	ds_read_b128 v[16:19], v25 offset:128
	ds_read_b128 v[20:23], v26 offset:128
	s_waitcnt lgkmcnt(1)
	v_mfma_f32_32x32x16_bf16 v[64:79], v[16:19], v[112:115], v[64:79]
	s_waitcnt lgkmcnt(0)
	v_mfma_f32_32x32x16_bf16 v[64:79], v[20:23], v[116:119], v[64:79]
	ds_read_b128 v[16:19], v27 offset:128
	ds_read_b128 v[20:23], v28 offset:128
	s_waitcnt lgkmcnt(1)
	v_mfma_f32_32x32x16_bf16 v[64:79], v[16:19], v[120:123], v[64:79]
	s_waitcnt lgkmcnt(0)
	v_mfma_f32_32x32x16_bf16 v[64:79], v[20:23], v[124:127], v[64:79]
	ds_read_b128 v[16:19], v25 offset:256
	ds_read_b128 v[20:23], v26 offset:256
	s_waitcnt lgkmcnt(1)
	v_mfma_f32_32x32x16_bf16 v[64:79], v[16:19], v[128:131], v[64:79]
	s_waitcnt lgkmcnt(0)
	v_mfma_f32_32x32x16_bf16 v[64:79], v[20:23], v[132:135], v[64:79]
	ds_read_b128 v[16:19], v27 offset:256
	ds_read_b128 v[20:23], v28 offset:256
	s_waitcnt lgkmcnt(1)
	v_mfma_f32_32x32x16_bf16 v[64:79], v[16:19], v[136:139], v[64:79]
	s_waitcnt lgkmcnt(0)
	v_mfma_f32_32x32x16_bf16 v[80:95], v[20:23], v[140:143], v[64:79]
	s_waitcnt lgkmcnt(0)
	s_barrier
	v_lshlrev_b32_e32 v198, 2, v24
	s_lshl_b32 s50, s40, 7
	v_readlane_b32 s0, v255, 54
	v_mov_b64_e32 v[30:31], v[14:15]
	v_mov_b64_e32 v[46:47], v[14:15]
	v_mov_b64_e32 v[62:63], v[14:15]
	v_lshl_add_u32 v203, v180, 7, 0
	s_mov_b32 s32, 0x12000
	v_add3_u32 v225, v203, v201, s32
	v_add3_u32 v245, v203, v202, s32
	s_add_i32 s51, s0, s50
	v_mov_b32_e32 v204, 0xf149f2ca
	v_mov_b32_e32 v226, 0
	v_mov_b32_e32 v227, v226
	v_mov_b32_e32 v228, v226
	v_mov_b32_e32 v229, v226
	v_mov_b32_e32 v230, v226
	v_mov_b32_e32 v231, v226
	v_mov_b32_e32 v232, v226
	v_mov_b32_e32 v233, v226
	v_mov_b32_e32 v234, v226
	v_mov_b32_e32 v235, v226
	v_mov_b32_e32 v236, v226
	v_mov_b32_e32 v237, v226
	v_mov_b32_e32 v238, v226
	v_mov_b32_e32 v239, v226
	v_mov_b32_e32 v240, v226
	v_mov_b32_e32 v241, v226
	v_mov_b32_e32 v242, 0xff7fffff
	v_mov_b32_e32 v243, 0
	v_mov_b64_e32 v[28:29], v[12:13]
	v_mov_b64_e32 v[26:27], v[10:11]
	v_mov_b64_e32 v[24:25], v[8:9]
	v_mov_b64_e32 v[22:23], v[6:7]
	v_mov_b64_e32 v[20:21], v[4:5]
	v_mov_b64_e32 v[18:19], v[2:3]
	v_mov_b64_e32 v[16:17], v[0:1]
	v_mov_b64_e32 v[44:45], v[12:13]
	v_mov_b64_e32 v[42:43], v[10:11]
	v_mov_b64_e32 v[40:41], v[8:9]
	v_mov_b64_e32 v[38:39], v[6:7]
	v_mov_b64_e32 v[36:37], v[4:5]
	v_mov_b64_e32 v[34:35], v[2:3]
	v_mov_b64_e32 v[32:33], v[0:1]
	v_mov_b64_e32 v[60:61], v[12:13]
	v_mov_b64_e32 v[58:59], v[10:11]
	v_mov_b64_e32 v[56:57], v[8:9]
	v_mov_b64_e32 v[54:55], v[6:7]
	v_mov_b64_e32 v[52:53], v[4:5]
	v_mov_b64_e32 v[50:51], v[2:3]
	v_mov_b64_e32 v[48:49], v[0:1]
	v_mov_b32_e32 v190, v177
	s_mov_b32 s0, s49
	s_mov_b32 s53, 2
	s_cmp_lt_i32 s51, 0
	s_mov_b32 s54, s0
	s_cbranch_scc1 .LBB0_477
	s_branch .LBB0_476

; #define LAS __attribute__((address_space(3)))
; __device__ __forceinline__ void attn_unit(LAS unsigned char* lds, const bf16_t* Qg, const bf16_t* Kg, const bf16_t* Vtg, bf16_t* Og, int bh, int qb, int tid_, int wave, int lane_) {
;     ...
;         if (__builtin_amdgcn_ballot_w64(mx > mrun + 8.f) != 0ull) {
;             const float mnew = fmaxf(mrun, mx); const float alpha = __builtin_amdgcn_exp2f(mrun - mnew); mrun = mnew; lrun *= alpha;
; #pragma unroll
;             for (int dt = 0; dt < 4; ++dt) o[dt] = o[dt] * alpha;
;         }
;         float ps = 0.f; u32x4 p0, p1;
; #pragma unroll
;         for (int q = 0; q < 4; ++q) sn = MFMA32(fb[q], qf[4 + q], sn);
; #pragma unroll
;         for (int i = 0; i < 8; ++i) { sc[i] = __builtin_amdgcn_exp2f(sc[i] - mrun); ps += sc[i]; }
;         p0.x = pk2(sc[0], sc[1]); p0.y = pk2(sc[2], sc[3]); p0.z = pk2(sc[4], sc[5]); p0.w = pk2(sc[6], sc[7]);
;         __builtin_amdgcn_sched_barrier(0);
; #pragma unroll
;         for (int dt = 0; dt < 4; ++dt) fb[dt] = *(const LAS bf16x8*)(vb + vro[0] + dt * 4096);
;         __builtin_amdgcn_sched_barrier(0);
;         ATT_ISSUE_K(j3, s0);
;         __builtin_amdgcn_sched_barrier(0);
; #pragma unroll
;         for (int q = 0; q < 4; ++q) sn = MFMA32(fa[q], qf[8 + q], sn);
; #pragma unroll
;         for (int i = 8; i < 12; ++i) { sc[i] = __builtin_amdgcn_exp2f(sc[i] - mrun); ps += sc[i]; }
;         p1.x = pk2(sc[8], sc[9]); p1.y = pk2(sc[10], sc[11]);
;         __builtin_amdgcn_sched_barrier(0);
;         ATT_ISSUE_V(j2, s2);
;         __builtin_amdgcn_sched_barrier(0);
; #pragma unroll
;         for (int dt = 0; dt < 4; ++dt) fa[dt] = *(const LAS bf16x8*)(vb + vro[1] + dt * 4096);
;         { const bf16x8 pf0 = __builtin_bit_cast(bf16x8, p0);
;           o[0] = MFMA32(fb[0], pf0, o[0]); o[1] = MFMA32(fb[1], pf0, o[1]); o[2] = MFMA32(fb[2], pf0, o[2]); o[3] = MFMA32(fb[3], pf0, o[3]); }
; #pragma unroll
;         for (int i = 12; i < 16; ++i) { sc[i] = __builtin_amdgcn_exp2f(sc[i] - mrun); ps += sc[i]; }
;         p1.z = pk2(sc[12], sc[13]); p1.w = pk2(sc[14], sc[15]);
;         lrun += ps;
;         __builtin_amdgcn_sched_barrier(0);
;         { const bf16x8 pf1 = __builtin_bit_cast(bf16x8, p1);
;           o[0] = MFMA32(fa[0], pf1, o[0]); o[1] = MFMA32(fa[1], pf1, o[1]); o[2] = MFMA32(fa[2], pf1, o[2]); o[3] = MFMA32(fa[3], pf1, o[3]); }
.LBB0_480:
	v_mfma_f32_32x32x16_bf16 v[64:79], v[164:167], v[112:115], v[64:79]
	v_exp_f32_e32 v192, v80
	v_exp_f32_e32 v193, v81
	v_exp_f32_e32 v194, v82
	s_waitcnt lgkmcnt(0)
	v_mfma_f32_32x32x16_bf16 v[64:79], v[172:175], v[116:119], v[64:79]
	v_exp_f32_e32 v205, v83
	v_exp_f32_e32 v206, v84
	v_exp_f32_e32 v207, v85
	v_exp_f32_e32 v208, v86
	v_mfma_f32_32x32x16_bf16 v[64:79], v[168:171], v[120:123], v[64:79]
	s_add_i32 s0, s52, 3
	v_exp_f32_e32 v209, v87
	s_cmp_lt_u32 s0, s89
	s_cselect_b32 s0, s0, s45
	s_add_i32 s1, s52, 2
	s_cmp_lt_u32 s52, s44
	s_cselect_b32 s48, s1, s45
	v_cvt_pk_bf16_f32 v246, v192, v193
	v_cvt_pk_bf16_f32 v247, v194, v205
	v_cvt_pk_bf16_f32 v248, v206, v207
	v_cvt_pk_bf16_f32 v249, v208, v209
	ds_read_b128 v[214:217], v225
	ds_read_b128 v[164:167], v225 offset:4096
	ds_read_b128 v[168:171], v225 offset:8192
	ds_read_b128 v[172:175], v225 offset:12288
	v_add_f32_e32 v192, v193, v192
	v_add_f32_e32 v192, v194, v192
	v_add_f32_e32 v192, v205, v192
	v_add_f32_e32 v192, v206, v192
	v_add_f32_e32 v192, v207, v192
	v_add_f32_e32 v192, v208, v192
	v_add_f32_e32 v194, v209, v192
	s_mul_hi_u32 s1, s0, 0x6000
	s_mulk_i32 s0, 0x6000
	s_add_u32 s0, s92, s0
	s_mul_i32 s4, s54, 0x6000
	s_addc_u32 s1, s93, s1
	s_add_i32 s4, s71, s4
	s_mov_b32 m0, s4
	s_waitcnt lgkmcnt(5)
	v_mfma_f32_32x32x16_bf16 v[64:79], v[160:163], v[124:127], v[64:79]
	global_load_lds_dwordx4 v176, s[0:1]
	s_add_i32 m0, s4, 0x400
	s_nop 0
	global_load_lds_dwordx4 v182, s[0:1]
	s_add_i32 m0, s4, 0x800
	s_nop 0
	global_load_lds_dwordx4 v184, s[0:1]
	v_mfma_f32_32x32x16_bf16 v[64:79], v[148:151], v[128:131], v[64:79]
	v_exp_f32_e32 v220, v88
	v_exp_f32_e32 v221, v89
	v_exp_f32_e32 v222, v90
	v_mfma_f32_32x32x16_bf16 v[64:79], v[156:159], v[132:135], v[64:79]
	v_exp_f32_e32 v223, v91
	v_add_f32_e32 v148, v220, v194
	v_add_f32_e32 v148, v221, v148
	v_add_f32_e32 v148, v222, v148
	v_add_f32_e32 v156, v223, v148
	v_cvt_pk_bf16_f32 v250, v220, v221
	v_cvt_pk_bf16_f32 v251, v222, v223
	v_mfma_f32_32x32x16_bf16 v[64:79], v[152:155], v[136:139], v[64:79]
	v_exp_f32_e32 v220, v92
	v_exp_f32_e32 v221, v93
	v_exp_f32_e32 v222, v94
	v_exp_f32_e32 v223, v95
	s_waitcnt lgkmcnt(0)
	v_mfma_f32_32x32x16_bf16 v[80:95], v[144:147], v[140:143], v[64:79]
	s_lshl_b64 s[0:1], s[48:49], 7
	s_add_u32 s0, s94, s0
	s_addc_u32 s1, s95, s1
	s_lshl_b32 s4, s53, 14
	s_add_i32 s4, s4, 0
	s_add_i32 s4, s4, s68
	s_add_i32 m0, s4, 0x12000
	s_nop 0
	global_load_lds_dwordx4 v186, s[0:1]
	s_add_i32 m0, s4, 0x12400
	s_nop 0
	global_load_lds_dwordx4 v188, s[0:1]
	v_mfma_f32_32x32x16_bf16 v[48:63], v[214:217], v[246:249], v[48:63]
	ds_read_b128 v[214:217], v245
	ds_read_b128 v[144:147], v245 offset:4096
	ds_read_b128 v[148:151], v245 offset:8192
	ds_read_b128 v[152:155], v245 offset:12288
	v_mfma_f32_32x32x16_bf16 v[32:47], v[164:167], v[246:249], v[32:47]
	v_add_f32_e32 v213, v220, v156
	v_add_f32_e32 v213, v221, v213
	v_add_f32_e32 v213, v222, v213
	v_add_f32_e32 v213, v223, v213
	v_add_f32_e32 v190, v190, v213
	v_mfma_f32_32x32x16_bf16 v[16:31], v[168:171], v[246:249], v[16:31]
	v_cvt_pk_bf16_f32 v252, v220, v221
	v_cvt_pk_bf16_f32 v253, v222, v223
	v_mfma_f32_32x32x16_bf16 v[0:15], v[172:175], v[246:249], v[0:15]
	s_waitcnt lgkmcnt(0)
	v_mfma_f32_32x32x16_bf16 v[48:63], v[214:217], v[250:253], v[48:63]
	s_waitcnt vmcnt(5) lgkmcnt(0)
	s_barrier
	s_add_i32 s52, s52, 1
	s_add_i32 s51, s51, 64
	s_cmp_eq_u32 s89, s52
	v_mfma_f32_32x32x16_bf16 v[32:47], v[144:147], v[250:253], v[32:47]
	v_mfma_f32_32x32x16_bf16 v[16:31], v[148:151], v[250:253], v[16:31]
	v_mfma_f32_32x32x16_bf16 v[0:15], v[152:155], v[250:253], v[0:15]
	s_cbranch_scc1 .LBB0_482
	s_mov_b32 s0, s84
	s_mov_b32 s84, s53
	s_mov_b32 s53, s54
	s_cmp_lt_i32 s51, 0
	s_mov_b32 s54, s0
	s_cbranch_scc0 .Latta_u1_476
.Latta_u1_477:
.Latta_u1_478:
	ds_read_b128 v[64:67], v191 offset:49152
	ds_read_b128 v[144:147], v197 offset:49152
	ds_read_b128 v[206:209], v200 offset:49152
	ds_read_b128 v[164:167], v191 offset:49280
	ds_read_b128 v[152:155], v199 offset:49152
	ds_read_b128 v[168:171], v199 offset:49280
	s_waitcnt lgkmcnt(0)
	v_mfma_f32_32x32x16_bf16 v[64:79], v[64:67], v[96:99], v[226:241]
	v_max_f32_e32 v149, v80, v81
	v_max3_f32 v157, v149, v82, v83
	ds_read_b128 v[148:151], v191 offset:49408
	s_waitcnt lgkmcnt(5)
	v_mfma_f32_32x32x16_bf16 v[64:79], v[144:147], v[100:103], v[64:79]
	v_max3_f32 v144, v157, v84, v85
	v_max3_f32 v144, v144, v86, v87
	v_max3_f32 v144, v144, v88, v89
	v_max3_f32 v144, v144, v90, v91
	v_max3_f32 v144, v144, v92, v93
	v_max3_f32 v193, v144, v94, v95
	s_waitcnt lgkmcnt(2)
	v_mfma_f32_32x32x16_bf16 v[64:79], v[152:155], v[104:107], v[64:79]
	ds_read_b128 v[172:175], v197 offset:49280
	ds_read_b128 v[156:159], v197 offset:49408
	ds_read_b128 v[152:155], v199 offset:49408
	ds_read_b128 v[160:163], v200 offset:49280
	ds_read_b128 v[144:147], v200 offset:49408
	v_mfma_f32_32x32x16_bf16 v[64:79], v[206:209], v[108:111], v[64:79]
	v_cmp_gt_f32_e32 vcc, v193, v242
	s_cbranch_vccz .Latta_u1_480
; __device__ __forceinline__ unsigned pk2(float a, float b) { f32x2_t v = {a, b}; bf16x2v_t r = __builtin_convertvector(v, bf16x2v_t); return __builtin_bit_cast(unsigned, r); }
; #define LAS __attribute__((address_space(3)))
; #define MFMA32(a, b, c) __builtin_amdgcn_mfma_f32_32x32x16_bf16((a), (b), (c), 0, 0, 0)
; #define ATT_ISSUE_K(jt, stage) do { _Pragma("unroll") for (int i_ = 0; i_ < 3; ++i_) ATT_DMA(kg + (size_t)(jt) * KTILE + kgo[i_], KRING + (stage) * KTILE + (wave * 3 + i_) * 1024); } while (0)
; __device__ __forceinline__ void attn_unit(LAS unsigned char* lds, const bf16_t* Qg, const bf16_t* Kg, const bf16_t* Vtg, bf16_t* Og, int bh, int qb, int tid_, int wave, int lane_) {
;     ...
;             const float mnew = fmaxf(mrun, mx); const float alpha = __builtin_amdgcn_exp2f(mrun - mnew); mrun = mnew; lrun *= alpha;
; #pragma unroll
;             for (int dt = 0; dt < 4; ++dt) o[dt] = o[dt] * alpha;
;         }
;         float ps = 0.f; u32x4 p0, p1;
; #pragma unroll
;         for (int q = 0; q < 4; ++q) sn = MFMA32(fb[q], qf[4 + q], sn);
; #pragma unroll
;         for (int i = 0; i < 8; ++i) { sc[i] = __builtin_amdgcn_exp2f(sc[i] - mrun); ps += sc[i]; }
;         p0.x = pk2(sc[0], sc[1]); p0.y = pk2(sc[2], sc[3]); p0.z = pk2(sc[4], sc[5]); p0.w = pk2(sc[6], sc[7]);
;         __builtin_amdgcn_sched_barrier(0);
; #pragma unroll
;         for (int dt = 0; dt < 4; ++dt) fb[dt] = *(const LAS bf16x8*)(vb + vro[0] + dt * 4096);
;         __builtin_amdgcn_sched_barrier(0);
;         ATT_ISSUE_K(j3, s0);
;         __builtin_amdgcn_sched_barrier(0);
; #pragma unroll
;         for (int q = 0; q < 4; ++q) sn = MFMA32(fa[q], qf[8 + q], sn);
; #pragma unroll
;         for (int i = 8; i < 12; ++i) { sc[i] = __builtin_amdgcn_exp2f(sc[i] - mrun); ps += sc[i]; }
;         p1.x = pk2(sc[8], sc[9]); p1.y = pk2(sc[10], sc[11]);
	v_mov_b32_e32 v194, v193
	s_nop 1
	v_permlane32_swap_b32_e32 v193, v194
	v_max_f32_e32 v205, v193, v194
	v_add_f32_e32 v192, v205, v243
	v_max_f32_e32 v193, v204, v204
	v_max_f32_e32 v193, v193, v192
	v_sub_f32_e32 v192, v204, v193
	v_sub_f32_e32 v244, v243, v193
	v_exp_f32_e32 v192, v192
	v_mov_b32_e32 v204, v193
	v_mov_b32_e32 v243, v193
	v_mov_b32_e32 v242, 0x41000000
	v_pk_mul_f32 v[62:63], v[62:63], v[192:193] op_sel_hi:[1,0]
	v_pk_mul_f32 v[60:61], v[60:61], v[192:193] op_sel_hi:[1,0]
	v_pk_mul_f32 v[58:59], v[58:59], v[192:193] op_sel_hi:[1,0]
	v_pk_mul_f32 v[56:57], v[56:57], v[192:193] op_sel_hi:[1,0]
	v_pk_mul_f32 v[54:55], v[54:55], v[192:193] op_sel_hi:[1,0]
	v_pk_mul_f32 v[52:53], v[52:53], v[192:193] op_sel_hi:[1,0]
	v_pk_mul_f32 v[50:51], v[50:51], v[192:193] op_sel_hi:[1,0]
	v_pk_mul_f32 v[48:49], v[48:49], v[192:193] op_sel_hi:[1,0]
	v_pk_mul_f32 v[46:47], v[46:47], v[192:193] op_sel_hi:[1,0]
	v_pk_mul_f32 v[44:45], v[44:45], v[192:193] op_sel_hi:[1,0]
	v_pk_mul_f32 v[42:43], v[42:43], v[192:193] op_sel_hi:[1,0]
	v_pk_mul_f32 v[40:41], v[40:41], v[192:193] op_sel_hi:[1,0]
	v_pk_mul_f32 v[38:39], v[38:39], v[192:193] op_sel_hi:[1,0]
	v_pk_mul_f32 v[36:37], v[36:37], v[192:193] op_sel_hi:[1,0]
	v_pk_mul_f32 v[34:35], v[34:35], v[192:193] op_sel_hi:[1,0]
	v_pk_mul_f32 v[32:33], v[32:33], v[192:193] op_sel_hi:[1,0]
	v_pk_mul_f32 v[30:31], v[30:31], v[192:193] op_sel_hi:[1,0]
	v_pk_mul_f32 v[28:29], v[28:29], v[192:193] op_sel_hi:[1,0]
	v_pk_mul_f32 v[26:27], v[26:27], v[192:193] op_sel_hi:[1,0]
	v_pk_mul_f32 v[24:25], v[24:25], v[192:193] op_sel_hi:[1,0]
	v_pk_mul_f32 v[22:23], v[22:23], v[192:193] op_sel_hi:[1,0]
	v_pk_mul_f32 v[20:21], v[20:21], v[192:193] op_sel_hi:[1,0]
	v_pk_mul_f32 v[18:19], v[18:19], v[192:193] op_sel_hi:[1,0]
	v_pk_mul_f32 v[16:17], v[16:17], v[192:193] op_sel_hi:[1,0]
	v_pk_mul_f32 v[14:15], v[14:15], v[192:193] op_sel_hi:[1,0]
	v_pk_mul_f32 v[12:13], v[12:13], v[192:193] op_sel_hi:[1,0]
	v_pk_mul_f32 v[10:11], v[10:11], v[192:193] op_sel_hi:[1,0]
	v_pk_mul_f32 v[8:9], v[8:9], v[192:193] op_sel_hi:[1,0]
	v_pk_mul_f32 v[6:7], v[6:7], v[192:193] op_sel_hi:[1,0]
	v_pk_mul_f32 v[4:5], v[4:5], v[192:193] op_sel_hi:[1,0]
	v_pk_mul_f32 v[2:3], v[2:3], v[192:193] op_sel_hi:[1,0]
	v_pk_mul_f32 v[0:1], v[0:1], v[192:193] op_sel_hi:[1,0]
	v_mul_f32_e32 v190, v190, v192
	v_add_f32_e32 v80, v80, v244
	v_add_f32_e32 v81, v81, v244
	v_add_f32_e32 v82, v82, v244
	v_add_f32_e32 v83, v83, v244
	v_add_f32_e32 v84, v84, v244
	v_add_f32_e32 v85, v85, v244
	v_add_f32_e32 v86, v86, v244
	v_add_f32_e32 v87, v87, v244
	v_add_f32_e32 v88, v88, v244
	v_add_f32_e32 v89, v89, v244
	v_add_f32_e32 v90, v90, v244
	v_add_f32_e32 v91, v91, v244
	v_add_f32_e32 v92, v92, v244
	v_add_f32_e32 v93, v93, v244
	v_add_f32_e32 v94, v94, v244
	v_add_f32_e32 v95, v95, v244
	v_add_f32_e32 v64, v64, v244
	v_add_f32_e32 v65, v65, v244
	v_add_f32_e32 v66, v66, v244
	v_add_f32_e32 v67, v67, v244
	v_add_f32_e32 v68, v68, v244
	v_add_f32_e32 v69, v69, v244
	v_add_f32_e32 v70, v70, v244
	v_add_f32_e32 v71, v71, v244
	v_add_f32_e32 v72, v72, v244
	v_add_f32_e32 v73, v73, v244
	v_add_f32_e32 v74, v74, v244
	v_add_f32_e32 v75, v75, v244
	v_add_f32_e32 v76, v76, v244
	v_add_f32_e32 v77, v77, v244
	v_add_f32_e32 v78, v78, v244
	v_add_f32_e32 v79, v79, v244
	v_sub_f32_e32 v226, 0, v193
	v_mov_b32_e32 v227, v226
	v_mov_b32_e32 v228, v226
	v_mov_b32_e32 v229, v226
	v_mov_b32_e32 v230, v226
	v_mov_b32_e32 v231, v226
	v_mov_b32_e32 v232, v226
	v_mov_b32_e32 v233, v226
	v_mov_b32_e32 v234, v226
	v_mov_b32_e32 v235, v226
	v_mov_b32_e32 v236, v226
	v_mov_b32_e32 v237, v226
	v_mov_b32_e32 v238, v226
	v_mov_b32_e32 v239, v226
	v_mov_b32_e32 v240, v226
	v_mov_b32_e32 v241, v226
.Latta_u1_480:
	v_mfma_f32_32x32x16_bf16 v[64:79], v[164:167], v[112:115], v[64:79]
	v_exp_f32_e32 v192, v80
	v_exp_f32_e32 v193, v81
	v_exp_f32_e32 v194, v82
	s_waitcnt lgkmcnt(0)
	v_mfma_f32_32x32x16_bf16 v[64:79], v[172:175], v[116:119], v[64:79]
	v_exp_f32_e32 v205, v83
	v_exp_f32_e32 v206, v84
	v_exp_f32_e32 v207, v85
	v_exp_f32_e32 v208, v86
	v_mfma_f32_32x32x16_bf16 v[64:79], v[168:171], v[120:123], v[64:79]
	s_add_i32 s0, s52, 3
	v_exp_f32_e32 v209, v87
	s_cmp_lt_u32 s0, s89
	s_cselect_b32 s0, s0, s45
	s_add_i32 s1, s52, 2
	s_cmp_lt_u32 s52, s44
	s_cselect_b32 s48, s1, s45
	v_cvt_pk_bf16_f32 v246, v192, v193
	v_cvt_pk_bf16_f32 v247, v194, v205
	v_cvt_pk_bf16_f32 v248, v206, v207
	v_cvt_pk_bf16_f32 v249, v208, v209
	ds_read_b128 v[214:217], v225 offset:16384
	ds_read_b128 v[164:167], v225 offset:20480
	ds_read_b128 v[168:171], v225 offset:24576
	ds_read_b128 v[172:175], v225 offset:28672
	v_add_f32_e32 v192, v193, v192
	v_add_f32_e32 v192, v194, v192
	v_add_f32_e32 v192, v205, v192
	v_add_f32_e32 v192, v206, v192
	v_add_f32_e32 v192, v207, v192
	v_add_f32_e32 v192, v208, v192
	v_add_f32_e32 v194, v209, v192
	s_mul_hi_u32 s1, s0, 0x6000
	s_mulk_i32 s0, 0x6000
	s_add_u32 s0, s92, s0
	s_mul_i32 s4, s54, 0x6000
	s_addc_u32 s1, s93, s1
	s_add_i32 s4, s71, s4
	s_mov_b32 m0, s4
	s_waitcnt lgkmcnt(5)
	v_mfma_f32_32x32x16_bf16 v[64:79], v[160:163], v[124:127], v[64:79]
	global_load_lds_dwordx4 v176, s[0:1]
	s_add_i32 m0, s4, 0x400
	s_nop 0
	global_load_lds_dwordx4 v182, s[0:1]
	s_add_i32 m0, s4, 0x800
	s_nop 0
	global_load_lds_dwordx4 v184, s[0:1]
	v_mfma_f32_32x32x16_bf16 v[64:79], v[148:151], v[128:131], v[64:79]
	v_exp_f32_e32 v220, v88
	v_exp_f32_e32 v221, v89
	v_exp_f32_e32 v222, v90
	v_mfma_f32_32x32x16_bf16 v[64:79], v[156:159], v[132:135], v[64:79]
	v_exp_f32_e32 v223, v91
	v_add_f32_e32 v148, v220, v194
	v_add_f32_e32 v148, v221, v148
	v_add_f32_e32 v148, v222, v148
	v_add_f32_e32 v156, v223, v148
	v_cvt_pk_bf16_f32 v250, v220, v221
	v_cvt_pk_bf16_f32 v251, v222, v223
	v_mfma_f32_32x32x16_bf16 v[64:79], v[152:155], v[136:139], v[64:79]
	v_exp_f32_e32 v220, v92
	v_exp_f32_e32 v221, v93
	v_exp_f32_e32 v222, v94
	v_exp_f32_e32 v223, v95
	s_waitcnt lgkmcnt(0)
; __device__ __forceinline__ void attn_unit(LAS unsigned char* lds, const bf16_t* Qg, const bf16_t* Kg, const bf16_t* Vtg, bf16_t* Og, int bh, int qb, int tid_, int wave, int lane_) {
;     ...
;     for (int j = 0; j < nt; ++j) {
;         const int relc = 64 * (j - 2 * qb) + 32 * kh - 32 * rg;
;         const int j3 = (j + 3 < nt) ? j + 3 : nt - 1, j2 = (j + 2 < nt) ? j + 2 : nt - 1;
;         const LAS unsigned char* kb = lds + KRING + s1 * KTILE;
;         const LAS unsigned char* vb = lds + s0 * VTILE;
;         if (relc >= 0) {
;             const int thr = (relc == 0) ? r : -1;
; #pragma unroll
;             for (int i = 0; i < 16; ++i) { const int key = (i & 3) + 8 * (i >> 2) + 4 * hi; if (key > thr) sc[i] = NINF; }
;         }
;     ...
;         bf16x8 fa[4], fb[4];
;         ATT_KRD(fa, 0); ATT_KRD(fb, 1);
; #pragma unroll
;         for (int i = 0; i < 16; ++i) sn[i] = 0.f;
;         float mx = sc[0];
; #pragma unroll
;         for (int i = 1; i < 16; ++i) mx = fmaxf(mx, sc[i]);
;         mx = max_xor32(mx);
; #pragma unroll
;         for (int q = 0; q < 4; ++q) sn = MFMA32(fa[q], qf[q], sn);
;         ATT_KRD(fa, 2);
;         __builtin_amdgcn_sched_barrier(0);
;         if (__builtin_amdgcn_ballot_w64(mx > mrun + 8.f) != 0ull) {
;     ...
;         __builtin_amdgcn_sched_barrier(0);
;         ATT_ISSUE_V(j2, s2);
;         __builtin_amdgcn_sched_barrier(0);
; #pragma unroll
;         for (int dt = 0; dt < 4; ++dt) fa[dt] = *(const LAS bf16x8*)(vb + vro[1] + dt * 4096);
;         { const bf16x8 pf0 = __builtin_bit_cast(bf16x8, p0);
;           o[0] = MFMA32(fb[0], pf0, o[0]); o[1] = MFMA32(fb[1], pf0, o[1]); o[2] = MFMA32(fb[2], pf0, o[2]); o[3] = MFMA32(fb[3], pf0, o[3]); }
; #pragma unroll
;         for (int i = 12; i < 16; ++i) { sc[i] = __builtin_amdgcn_exp2f(sc[i] - mrun); ps += sc[i]; }
;         p1.z = pk2(sc[12], sc[13]); p1.w = pk2(sc[14], sc[15]);
;         lrun += ps;
;         __builtin_amdgcn_sched_barrier(0);
;         { const bf16x8 pf1 = __builtin_bit_cast(bf16x8, p1);
;           o[0] = MFMA32(fa[0], pf1, o[0]); o[1] = MFMA32(fa[1], pf1, o[1]); o[2] = MFMA32(fa[2], pf1, o[2]); o[3] = MFMA32(fa[3], pf1, o[3]); }
;         asm volatile("s_waitcnt vmcnt(5) lgkmcnt(0)" ::: "memory"); __builtin_amdgcn_s_barrier(); asm volatile("" ::: "memory");
;         sc = sn;
;         { const int t = s0; s0 = s1; s1 = s2; s2 = t; }
;     }
	v_mfma_f32_32x32x16_bf16 v[80:95], v[144:147], v[140:143], v[64:79]
	s_lshl_b64 s[0:1], s[48:49], 7
	s_add_u32 s0, s94, s0
	s_addc_u32 s1, s95, s1
	s_lshl_b32 s4, s53, 14
	s_add_i32 s4, s4, 0
	s_add_i32 s4, s4, s68
	s_add_i32 m0, s4, 0x12000
	s_nop 0
	global_load_lds_dwordx4 v186, s[0:1]
	s_add_i32 m0, s4, 0x12400
	s_nop 0
	global_load_lds_dwordx4 v188, s[0:1]
	v_mfma_f32_32x32x16_bf16 v[48:63], v[214:217], v[246:249], v[48:63]
	ds_read_b128 v[214:217], v245 offset:16384
	ds_read_b128 v[144:147], v245 offset:20480
	ds_read_b128 v[148:151], v245 offset:24576
	ds_read_b128 v[152:155], v245 offset:28672
	v_mfma_f32_32x32x16_bf16 v[32:47], v[164:167], v[246:249], v[32:47]
	v_add_f32_e32 v213, v220, v156
	v_add_f32_e32 v213, v221, v213
	v_add_f32_e32 v213, v222, v213
	v_add_f32_e32 v213, v223, v213
	v_add_f32_e32 v190, v190, v213
	v_mfma_f32_32x32x16_bf16 v[16:31], v[168:171], v[246:249], v[16:31]
	v_cvt_pk_bf16_f32 v252, v220, v221
	v_cvt_pk_bf16_f32 v253, v222, v223
	v_mfma_f32_32x32x16_bf16 v[0:15], v[172:175], v[246:249], v[0:15]
	s_waitcnt lgkmcnt(0)
	v_mfma_f32_32x32x16_bf16 v[48:63], v[214:217], v[250:253], v[48:63]
	s_waitcnt vmcnt(5) lgkmcnt(0)
	s_barrier
	s_add_i32 s52, s52, 1
	s_add_i32 s51, s51, 64
	s_cmp_eq_u32 s89, s52
	v_mfma_f32_32x32x16_bf16 v[32:47], v[144:147], v[250:253], v[32:47]
	v_mfma_f32_32x32x16_bf16 v[16:31], v[148:151], v[250:253], v[16:31]
	v_mfma_f32_32x32x16_bf16 v[0:15], v[152:155], v[250:253], v[0:15]
	s_cbranch_scc1 .LBB0_482
	s_mov_b32 s0, s84
	s_mov_b32 s84, s53
	s_mov_b32 s53, s54
	s_cmp_lt_i32 s51, 0
	s_mov_b32 s54, s0
	s_cbranch_scc0 .Latta_u2_476
.Latta_u2_477:
.Latta_u2_478:
	ds_read_b128 v[64:67], v191
	ds_read_b128 v[144:147], v197
	ds_read_b128 v[206:209], v200
	ds_read_b128 v[164:167], v191 offset:128
	ds_read_b128 v[152:155], v199
	ds_read_b128 v[168:171], v199 offset:128
	s_waitcnt lgkmcnt(0)
	v_mfma_f32_32x32x16_bf16 v[64:79], v[64:67], v[96:99], v[226:241]
	v_max_f32_e32 v149, v80, v81
	v_max3_f32 v157, v149, v82, v83
	ds_read_b128 v[148:151], v191 offset:256
	s_waitcnt lgkmcnt(5)
	v_mfma_f32_32x32x16_bf16 v[64:79], v[144:147], v[100:103], v[64:79]
	v_max3_f32 v144, v157, v84, v85
	v_max3_f32 v144, v144, v86, v87
	v_max3_f32 v144, v144, v88, v89
	v_max3_f32 v144, v144, v90, v91
	v_max3_f32 v144, v144, v92, v93
	v_max3_f32 v193, v144, v94, v95
	s_waitcnt lgkmcnt(2)
	v_mfma_f32_32x32x16_bf16 v[64:79], v[152:155], v[104:107], v[64:79]
	ds_read_b128 v[172:175], v197 offset:128
	ds_read_b128 v[156:159], v197 offset:256
	ds_read_b128 v[152:155], v199 offset:256
	ds_read_b128 v[160:163], v200 offset:128
	ds_read_b128 v[144:147], v200 offset:256
	v_mfma_f32_32x32x16_bf16 v[64:79], v[206:209], v[108:111], v[64:79]
	v_cmp_gt_f32_e32 vcc, v193, v242
	s_cbranch_vccz .Latta_u2_480
	v_mov_b32_e32 v194, v193
	s_nop 1
	v_permlane32_swap_b32_e32 v193, v194
	v_max_f32_e32 v205, v193, v194
	v_add_f32_e32 v192, v205, v243
	v_max_f32_e32 v193, v204, v204
	v_max_f32_e32 v193, v193, v192
	v_sub_f32_e32 v192, v204, v193
	v_sub_f32_e32 v244, v243, v193
	v_exp_f32_e32 v192, v192
	v_mov_b32_e32 v204, v193
	v_mov_b32_e32 v243, v193
	v_mov_b32_e32 v242, 0x41000000
	v_pk_mul_f32 v[62:63], v[62:63], v[192:193] op_sel_hi:[1,0]
	v_pk_mul_f32 v[60:61], v[60:61], v[192:193] op_sel_hi:[1,0]
	v_pk_mul_f32 v[58:59], v[58:59], v[192:193] op_sel_hi:[1,0]
	v_pk_mul_f32 v[56:57], v[56:57], v[192:193] op_sel_hi:[1,0]
	v_pk_mul_f32 v[54:55], v[54:55], v[192:193] op_sel_hi:[1,0]
	v_pk_mul_f32 v[52:53], v[52:53], v[192:193] op_sel_hi:[1,0]
	v_pk_mul_f32 v[50:51], v[50:51], v[192:193] op_sel_hi:[1,0]
	v_pk_mul_f32 v[48:49], v[48:49], v[192:193] op_sel_hi:[1,0]
	v_pk_mul_f32 v[46:47], v[46:47], v[192:193] op_sel_hi:[1,0]
	v_pk_mul_f32 v[44:45], v[44:45], v[192:193] op_sel_hi:[1,0]
	v_pk_mul_f32 v[42:43], v[42:43], v[192:193] op_sel_hi:[1,0]
	v_pk_mul_f32 v[40:41], v[40:41], v[192:193] op_sel_hi:[1,0]
	v_pk_mul_f32 v[38:39], v[38:39], v[192:193] op_sel_hi:[1,0]
	v_pk_mul_f32 v[36:37], v[36:37], v[192:193] op_sel_hi:[1,0]
	v_pk_mul_f32 v[34:35], v[34:35], v[192:193] op_sel_hi:[1,0]
	v_pk_mul_f32 v[32:33], v[32:33], v[192:193] op_sel_hi:[1,0]
	v_pk_mul_f32 v[30:31], v[30:31], v[192:193] op_sel_hi:[1,0]
	v_pk_mul_f32 v[28:29], v[28:29], v[192:193] op_sel_hi:[1,0]
	v_pk_mul_f32 v[26:27], v[26:27], v[192:193] op_sel_hi:[1,0]
	v_pk_mul_f32 v[24:25], v[24:25], v[192:193] op_sel_hi:[1,0]
	v_pk_mul_f32 v[22:23], v[22:23], v[192:193] op_sel_hi:[1,0]
	v_pk_mul_f32 v[20:21], v[20:21], v[192:193] op_sel_hi:[1,0]
	v_pk_mul_f32 v[18:19], v[18:19], v[192:193] op_sel_hi:[1,0]
	v_pk_mul_f32 v[16:17], v[16:17], v[192:193] op_sel_hi:[1,0]
	v_pk_mul_f32 v[14:15], v[14:15], v[192:193] op_sel_hi:[1,0]
	v_pk_mul_f32 v[12:13], v[12:13], v[192:193] op_sel_hi:[1,0]
	v_pk_mul_f32 v[10:11], v[10:11], v[192:193] op_sel_hi:[1,0]
	v_pk_mul_f32 v[8:9], v[8:9], v[192:193] op_sel_hi:[1,0]
	v_pk_mul_f32 v[6:7], v[6:7], v[192:193] op_sel_hi:[1,0]
	v_pk_mul_f32 v[4:5], v[4:5], v[192:193] op_sel_hi:[1,0]
	v_pk_mul_f32 v[2:3], v[2:3], v[192:193] op_sel_hi:[1,0]
	v_pk_mul_f32 v[0:1], v[0:1], v[192:193] op_sel_hi:[1,0]
	v_mul_f32_e32 v190, v190, v192
	v_add_f32_e32 v80, v80, v244
	v_add_f32_e32 v81, v81, v244
	v_add_f32_e32 v82, v82, v244
	v_add_f32_e32 v83, v83, v244
	v_add_f32_e32 v84, v84, v244
	v_add_f32_e32 v85, v85, v244
	v_add_f32_e32 v86, v86, v244
	v_add_f32_e32 v87, v87, v244
	v_add_f32_e32 v88, v88, v244
	v_add_f32_e32 v89, v89, v244
	v_add_f32_e32 v90, v90, v244
	v_add_f32_e32 v91, v91, v244
	v_add_f32_e32 v92, v92, v244
	v_add_f32_e32 v93, v93, v244
	v_add_f32_e32 v94, v94, v244
	v_add_f32_e32 v95, v95, v244
	v_add_f32_e32 v64, v64, v244
	v_add_f32_e32 v65, v65, v244
	v_add_f32_e32 v66, v66, v244
	v_add_f32_e32 v67, v67, v244
	v_add_f32_e32 v68, v68, v244
	v_add_f32_e32 v69, v69, v244
	v_add_f32_e32 v70, v70, v244
	v_add_f32_e32 v71, v71, v244
	v_add_f32_e32 v72, v72, v244
	v_add_f32_e32 v73, v73, v244
	v_add_f32_e32 v74, v74, v244
	v_add_f32_e32 v75, v75, v244
	v_add_f32_e32 v76, v76, v244
	v_add_f32_e32 v77, v77, v244
	v_add_f32_e32 v78, v78, v244
	v_add_f32_e32 v79, v79, v244
	v_sub_f32_e32 v226, 0, v193
	v_mov_b32_e32 v227, v226
	v_mov_b32_e32 v228, v226
	v_mov_b32_e32 v229, v226
	v_mov_b32_e32 v230, v226
	v_mov_b32_e32 v231, v226
	v_mov_b32_e32 v232, v226
	v_mov_b32_e32 v233, v226
	v_mov_b32_e32 v234, v226
	v_mov_b32_e32 v235, v226
	v_mov_b32_e32 v236, v226
	v_mov_b32_e32 v237, v226
	v_mov_b32_e32 v238, v226
	v_mov_b32_e32 v239, v226
	v_mov_b32_e32 v240, v226
	v_mov_b32_e32 v241, v226
; #define LAS __attribute__((address_space(3)))
; __device__ __forceinline__ void attn_unit(LAS unsigned char* lds, const bf16_t* Qg, const bf16_t* Kg, const bf16_t* Vtg, bf16_t* Og, int bh, int qb, int tid_, int wave, int lane_) {
;     ...
;         if (relc >= 0) {
;             const int thr = (relc == 0) ? r : -1;
; #pragma unroll
;     ...
;         float ps = 0.f; u32x4 p0, p1;
; #pragma unroll
;         for (int q = 0; q < 4; ++q) sn = MFMA32(fb[q], qf[4 + q], sn);
; #pragma unroll
;         for (int i = 0; i < 8; ++i) { sc[i] = __builtin_amdgcn_exp2f(sc[i] - mrun); ps += sc[i]; }
;         p0.x = pk2(sc[0], sc[1]); p0.y = pk2(sc[2], sc[3]); p0.z = pk2(sc[4], sc[5]); p0.w = pk2(sc[6], sc[7]);
;         __builtin_amdgcn_sched_barrier(0);
; #pragma unroll
;         for (int dt = 0; dt < 4; ++dt) fb[dt] = *(const LAS bf16x8*)(vb + vro[0] + dt * 4096);
;         __builtin_amdgcn_sched_barrier(0);
;         ATT_ISSUE_K(j3, s0);
;         __builtin_amdgcn_sched_barrier(0);
; #pragma unroll
;         for (int q = 0; q < 4; ++q) sn = MFMA32(fa[q], qf[8 + q], sn);
; #pragma unroll
;         for (int i = 8; i < 12; ++i) { sc[i] = __builtin_amdgcn_exp2f(sc[i] - mrun); ps += sc[i]; }
;         p1.x = pk2(sc[8], sc[9]); p1.y = pk2(sc[10], sc[11]);
;         __builtin_amdgcn_sched_barrier(0);
;         ATT_ISSUE_V(j2, s2);
;         __builtin_amdgcn_sched_barrier(0);
; #pragma unroll
;         for (int dt = 0; dt < 4; ++dt) fa[dt] = *(const LAS bf16x8*)(vb + vro[1] + dt * 4096);
;         { const bf16x8 pf0 = __builtin_bit_cast(bf16x8, p0);
;           o[0] = MFMA32(fb[0], pf0, o[0]); o[1] = MFMA32(fb[1], pf0, o[1]); o[2] = MFMA32(fb[2], pf0, o[2]); o[3] = MFMA32(fb[3], pf0, o[3]); }
; #pragma unroll
;         for (int i = 12; i < 16; ++i) { sc[i] = __builtin_amdgcn_exp2f(sc[i] - mrun); ps += sc[i]; }
;         p1.z = pk2(sc[12], sc[13]); p1.w = pk2(sc[14], sc[15]);
;         lrun += ps;
;         __builtin_amdgcn_sched_barrier(0);
;         { const bf16x8 pf1 = __builtin_bit_cast(bf16x8, p1);
;           o[0] = MFMA32(fa[0], pf1, o[0]); o[1] = MFMA32(fa[1], pf1, o[1]); o[2] = MFMA32(fa[2], pf1, o[2]); o[3] = MFMA32(fa[3], pf1, o[3]); }
;         asm volatile("s_waitcnt vmcnt(5) lgkmcnt(0)" ::: "memory"); __builtin_amdgcn_s_barrier(); asm volatile("" ::: "memory");
;         sc = sn;
;         { const int t = s0; s0 = s1; s1 = s2; s2 = t; }
;     }
.Latta_u2_480:
	v_mfma_f32_32x32x16_bf16 v[64:79], v[164:167], v[112:115], v[64:79]
	v_exp_f32_e32 v192, v80
	v_exp_f32_e32 v193, v81
	v_exp_f32_e32 v194, v82
	s_waitcnt lgkmcnt(0)
	v_mfma_f32_32x32x16_bf16 v[64:79], v[172:175], v[116:119], v[64:79]
	v_exp_f32_e32 v205, v83
	v_exp_f32_e32 v206, v84
	v_exp_f32_e32 v207, v85
	v_exp_f32_e32 v208, v86
	v_mfma_f32_32x32x16_bf16 v[64:79], v[168:171], v[120:123], v[64:79]
	s_add_i32 s0, s52, 3
	v_exp_f32_e32 v209, v87
	s_cmp_lt_u32 s0, s89
	s_cselect_b32 s0, s0, s45
	s_add_i32 s1, s52, 2
	s_cmp_lt_u32 s52, s44
	s_cselect_b32 s48, s1, s45
	v_cvt_pk_bf16_f32 v246, v192, v193
	v_cvt_pk_bf16_f32 v247, v194, v205
	v_cvt_pk_bf16_f32 v248, v206, v207
	v_cvt_pk_bf16_f32 v249, v208, v209
	ds_read_b128 v[214:217], v225 offset:32768
	ds_read_b128 v[164:167], v225 offset:36864
	ds_read_b128 v[168:171], v225 offset:40960
	ds_read_b128 v[172:175], v225 offset:45056
	v_add_f32_e32 v192, v193, v192
	v_add_f32_e32 v192, v194, v192
	v_add_f32_e32 v192, v205, v192
	v_add_f32_e32 v192, v206, v192
	v_add_f32_e32 v192, v207, v192
	v_add_f32_e32 v192, v208, v192
	v_add_f32_e32 v194, v209, v192
	s_mul_hi_u32 s1, s0, 0x6000
	s_mulk_i32 s0, 0x6000
	s_add_u32 s0, s92, s0
	s_mul_i32 s4, s54, 0x6000
	s_addc_u32 s1, s93, s1
	s_add_i32 s4, s71, s4
	s_mov_b32 m0, s4
	s_waitcnt lgkmcnt(5)
	v_mfma_f32_32x32x16_bf16 v[64:79], v[160:163], v[124:127], v[64:79]
	global_load_lds_dwordx4 v176, s[0:1]
	s_add_i32 m0, s4, 0x400
	s_nop 0
	global_load_lds_dwordx4 v182, s[0:1]
	s_add_i32 m0, s4, 0x800
	s_nop 0
	global_load_lds_dwordx4 v184, s[0:1]
	v_mfma_f32_32x32x16_bf16 v[64:79], v[148:151], v[128:131], v[64:79]
	v_exp_f32_e32 v220, v88
	v_exp_f32_e32 v221, v89
	v_exp_f32_e32 v222, v90
	v_mfma_f32_32x32x16_bf16 v[64:79], v[156:159], v[132:135], v[64:79]
	v_exp_f32_e32 v223, v91
	v_add_f32_e32 v148, v220, v194
	v_add_f32_e32 v148, v221, v148
	v_add_f32_e32 v148, v222, v148
	v_add_f32_e32 v156, v223, v148
	v_cvt_pk_bf16_f32 v250, v220, v221
	v_cvt_pk_bf16_f32 v251, v222, v223
	v_mfma_f32_32x32x16_bf16 v[64:79], v[152:155], v[136:139], v[64:79]
	v_exp_f32_e32 v220, v92
	v_exp_f32_e32 v221, v93
	v_exp_f32_e32 v222, v94
	v_exp_f32_e32 v223, v95
	s_waitcnt lgkmcnt(0)
	v_mfma_f32_32x32x16_bf16 v[80:95], v[144:147], v[140:143], v[64:79]
	s_lshl_b64 s[0:1], s[48:49], 7
	s_add_u32 s0, s94, s0
	s_addc_u32 s1, s95, s1
	s_lshl_b32 s4, s53, 14
	s_add_i32 s4, s4, 0
	s_add_i32 s4, s4, s68
	s_add_i32 m0, s4, 0x12000
	s_nop 0
	global_load_lds_dwordx4 v186, s[0:1]
	s_add_i32 m0, s4, 0x12400
	s_nop 0
	global_load_lds_dwordx4 v188, s[0:1]
	v_mfma_f32_32x32x16_bf16 v[48:63], v[214:217], v[246:249], v[48:63]
	ds_read_b128 v[214:217], v245 offset:32768
	ds_read_b128 v[144:147], v245 offset:36864
	ds_read_b128 v[148:151], v245 offset:40960
	ds_read_b128 v[152:155], v245 offset:45056
	v_mfma_f32_32x32x16_bf16 v[32:47], v[164:167], v[246:249], v[32:47]
	v_add_f32_e32 v213, v220, v156
	v_add_f32_e32 v213, v221, v213
	v_add_f32_e32 v213, v222, v213
	v_add_f32_e32 v213, v223, v213
	v_add_f32_e32 v190, v190, v213
	v_mfma_f32_32x32x16_bf16 v[16:31], v[168:171], v[246:249], v[16:31]
	v_cvt_pk_bf16_f32 v252, v220, v221
	v_cvt_pk_bf16_f32 v253, v222, v223
	v_mfma_f32_32x32x16_bf16 v[0:15], v[172:175], v[246:249], v[0:15]
	s_waitcnt lgkmcnt(0)
	v_mfma_f32_32x32x16_bf16 v[48:63], v[214:217], v[250:253], v[48:63]
	s_waitcnt vmcnt(5) lgkmcnt(0)
	s_barrier
	s_add_i32 s52, s52, 1
	s_add_i32 s51, s51, 64
	s_cmp_eq_u32 s89, s52
	v_mfma_f32_32x32x16_bf16 v[32:47], v[144:147], v[250:253], v[32:47]
	v_mfma_f32_32x32x16_bf16 v[16:31], v[148:151], v[250:253], v[16:31]
	v_mfma_f32_32x32x16_bf16 v[0:15], v[152:155], v[250:253], v[0:15]
	s_cbranch_scc1 .LBB0_482
	s_mov_b32 s0, s84
	s_mov_b32 s84, s53
	s_mov_b32 s53, s54
	s_cmp_lt_i32 s51, 0
	s_mov_b32 s54, s0
	s_cbranch_scc0 .LBB0_476
	s_branch .LBB0_477
.LBB0_476:
	s_cmp_eq_u32 s51, 0
	s_cselect_b64 vcc, -1, 0
	v_cndmask_b32_e32 v213, -1, v180, vcc
	v_sub_u32_e32 v213, v213, v198
	v_cmp_gt_i32_e64 s[34:35], 26, v213
	v_cmp_gt_i32_e64 s[36:37], 27, v213
	v_cmp_gt_i32_e64 s[30:31], 25, v213
	s_and_b64 s[34:35], s[36:37], s[34:35]
	v_cmp_gt_i32_e64 s[28:29], 24, v213
	s_and_b64 s[30:31], s[34:35], s[30:31]
	v_cmp_gt_i32_e64 s[26:27], 19, v213
	s_and_b64 s[28:29], s[30:31], s[28:29]
	v_cmp_gt_i32_e64 s[24:25], 18, v213
	s_and_b64 s[26:27], s[28:29], s[26:27]
	v_cmp_gt_i32_e64 s[22:23], 17, v213
	s_and_b64 s[24:25], s[26:27], s[24:25]
	v_cmp_gt_i32_e64 s[20:21], 16, v213
	s_and_b64 s[22:23], s[24:25], s[22:23]
	v_cmp_gt_i32_e64 s[18:19], 11, v213
	s_and_b64 s[20:21], s[22:23], s[20:21]
	v_cmp_gt_i32_e64 s[16:17], 10, v213
	s_and_b64 s[18:19], s[20:21], s[18:19]
	v_cmp_gt_i32_e64 s[14:15], 9, v213
	s_and_b64 s[16:17], s[18:19], s[16:17]
	v_cmp_gt_i32_e64 s[12:13], 8, v213
	s_and_b64 s[14:15], s[16:17], s[14:15]
	v_cmp_gt_i32_e64 s[6:7], 3, v213
	s_and_b64 s[12:13], s[14:15], s[12:13]
	v_cmp_gt_i32_e64 s[4:5], 2, v213
	s_and_b64 s[6:7], s[12:13], s[6:7]
	v_cmp_gt_i32_e64 s[0:1], 1, v213
	s_and_b64 s[4:5], s[6:7], s[4:5]
	v_cmp_gt_i32_e32 vcc, 0, v213
	s_and_b64 s[0:1], s[4:5], s[0:1]
	s_and_b64 vcc, s[0:1], vcc
	v_cndmask_b32_e64 v95, v95, v196, s[36:37]
	v_cndmask_b32_e64 v94, v94, v196, s[34:35]
	v_cndmask_b32_e64 v93, v93, v196, s[30:31]
	v_cndmask_b32_e64 v92, v92, v196, s[28:29]
	v_cndmask_b32_e64 v91, v91, v196, s[26:27]
	v_cndmask_b32_e64 v90, v90, v196, s[24:25]
	v_cndmask_b32_e64 v89, v89, v196, s[22:23]
	v_cndmask_b32_e64 v88, v88, v196, s[20:21]
	v_cndmask_b32_e64 v87, v87, v196, s[18:19]
	v_cndmask_b32_e64 v86, v86, v196, s[16:17]
	v_cndmask_b32_e64 v85, v85, v196, s[14:15]
	v_cndmask_b32_e64 v84, v84, v196, s[12:13]
	v_cndmask_b32_e64 v83, v83, v196, s[6:7]
	v_cndmask_b32_e64 v82, v82, v196, s[4:5]
	v_cndmask_b32_e64 v81, v81, v196, s[0:1]
	v_cndmask_b32_e32 v80, v80, v196, vcc
	s_branch .LBB0_478
; #define LAS __attribute__((address_space(3)))
; __device__ __forceinline__ void attn_unit(LAS unsigned char* lds, const bf16_t* Qg, const bf16_t* Kg, const bf16_t* Vtg, bf16_t* Og, int bh, int qb, int tid_, int wave, int lane_) {
;     ...
;         if (relc >= 0) {
;             const int thr = (relc == 0) ? r : -1;
; #pragma unroll
;             for (int i = 0; i < 16; ++i) { const int key = (i & 3) + 8 * (i >> 2) + 4 * hi; if (key > thr) sc[i] = NINF; }
;         }
;     ...
;     asm volatile("s_waitcnt vmcnt(0) lgkmcnt(0)" ::: "memory"); __builtin_amdgcn_s_barrier(); asm volatile("" ::: "memory");
;     LAS float* cs = (LAS float*)(lds + rg * (66 * 64 * 4)) + lane;
;     if (kh == 1) {
; #pragma unroll
;         for (int dt = 0; dt < 4; ++dt)
; #pragma unroll
;             for (int i = 0; i < 16; ++i) cs[(dt * 16 + i) * 64] = o[dt][i];
;         cs[64 * 64] = mrun; cs[65 * 64] = lrun;
;     }
.Latta_u1_476:
	s_cmp_eq_u32 s51, 0
	s_cselect_b64 vcc, -1, 0
	v_cndmask_b32_e32 v213, -1, v180, vcc
	v_sub_u32_e32 v213, v213, v198
	v_cmp_gt_i32_e64 s[34:35], 26, v213
	v_cmp_gt_i32_e64 s[36:37], 27, v213
	v_cmp_gt_i32_e64 s[30:31], 25, v213
	s_and_b64 s[34:35], s[36:37], s[34:35]
	v_cmp_gt_i32_e64 s[28:29], 24, v213
	s_and_b64 s[30:31], s[34:35], s[30:31]
	v_cmp_gt_i32_e64 s[26:27], 19, v213
	s_and_b64 s[28:29], s[30:31], s[28:29]
	v_cmp_gt_i32_e64 s[24:25], 18, v213
	s_and_b64 s[26:27], s[28:29], s[26:27]
	v_cmp_gt_i32_e64 s[22:23], 17, v213
	s_and_b64 s[24:25], s[26:27], s[24:25]
	v_cmp_gt_i32_e64 s[20:21], 16, v213
	s_and_b64 s[22:23], s[24:25], s[22:23]
	v_cmp_gt_i32_e64 s[18:19], 11, v213
	s_and_b64 s[20:21], s[22:23], s[20:21]
	v_cmp_gt_i32_e64 s[16:17], 10, v213
	s_and_b64 s[18:19], s[20:21], s[18:19]
	v_cmp_gt_i32_e64 s[14:15], 9, v213
	s_and_b64 s[16:17], s[18:19], s[16:17]
	v_cmp_gt_i32_e64 s[12:13], 8, v213
	s_and_b64 s[14:15], s[16:17], s[14:15]
	v_cmp_gt_i32_e64 s[6:7], 3, v213
	s_and_b64 s[12:13], s[14:15], s[12:13]
	v_cmp_gt_i32_e64 s[4:5], 2, v213
	s_and_b64 s[6:7], s[12:13], s[6:7]
	v_cmp_gt_i32_e64 s[0:1], 1, v213
	s_and_b64 s[4:5], s[6:7], s[4:5]
	v_cmp_gt_i32_e32 vcc, 0, v213
	s_and_b64 s[0:1], s[4:5], s[0:1]
	s_and_b64 vcc, s[0:1], vcc
	v_cndmask_b32_e64 v95, v95, v196, s[36:37]
	v_cndmask_b32_e64 v94, v94, v196, s[34:35]
	v_cndmask_b32_e64 v93, v93, v196, s[30:31]
	v_cndmask_b32_e64 v92, v92, v196, s[28:29]
	v_cndmask_b32_e64 v91, v91, v196, s[26:27]
	v_cndmask_b32_e64 v90, v90, v196, s[24:25]
	v_cndmask_b32_e64 v89, v89, v196, s[22:23]
	v_cndmask_b32_e64 v88, v88, v196, s[20:21]
	v_cndmask_b32_e64 v87, v87, v196, s[18:19]
	v_cndmask_b32_e64 v86, v86, v196, s[16:17]
	v_cndmask_b32_e64 v85, v85, v196, s[14:15]
	v_cndmask_b32_e64 v84, v84, v196, s[12:13]
	v_cndmask_b32_e64 v83, v83, v196, s[6:7]
	v_cndmask_b32_e64 v82, v82, v196, s[4:5]
	v_cndmask_b32_e64 v81, v81, v196, s[0:1]
	v_cndmask_b32_e32 v80, v80, v196, vcc
	s_branch .Latta_u1_478
.Latta_u2_476:
	s_cmp_eq_u32 s51, 0
	s_cselect_b64 vcc, -1, 0
	v_cndmask_b32_e32 v213, -1, v180, vcc
	v_sub_u32_e32 v213, v213, v198
	v_cmp_gt_i32_e64 s[34:35], 26, v213
	v_cmp_gt_i32_e64 s[36:37], 27, v213
	v_cmp_gt_i32_e64 s[30:31], 25, v213
	s_and_b64 s[34:35], s[36:37], s[34:35]
	v_cmp_gt_i32_e64 s[28:29], 24, v213
	s_and_b64 s[30:31], s[34:35], s[30:31]
	v_cmp_gt_i32_e64 s[26:27], 19, v213
	s_and_b64 s[28:29], s[30:31], s[28:29]
	v_cmp_gt_i32_e64 s[24:25], 18, v213
	s_and_b64 s[26:27], s[28:29], s[26:27]
	v_cmp_gt_i32_e64 s[22:23], 17, v213
	s_and_b64 s[24:25], s[26:27], s[24:25]
	v_cmp_gt_i32_e64 s[20:21], 16, v213
	s_and_b64 s[22:23], s[24:25], s[22:23]
	v_cmp_gt_i32_e64 s[18:19], 11, v213
	s_and_b64 s[20:21], s[22:23], s[20:21]
	v_cmp_gt_i32_e64 s[16:17], 10, v213
	s_and_b64 s[18:19], s[20:21], s[18:19]
	v_cmp_gt_i32_e64 s[14:15], 9, v213
	s_and_b64 s[16:17], s[18:19], s[16:17]
	v_cmp_gt_i32_e64 s[12:13], 8, v213
	s_and_b64 s[14:15], s[16:17], s[14:15]
	v_cmp_gt_i32_e64 s[6:7], 3, v213
	s_and_b64 s[12:13], s[14:15], s[12:13]
	v_cmp_gt_i32_e64 s[4:5], 2, v213
	s_and_b64 s[6:7], s[12:13], s[6:7]
	v_cmp_gt_i32_e64 s[0:1], 1, v213
	s_and_b64 s[4:5], s[6:7], s[4:5]
	v_cmp_gt_i32_e32 vcc, 0, v213
	s_and_b64 s[0:1], s[4:5], s[0:1]
	s_and_b64 vcc, s[0:1], vcc
	v_cndmask_b32_e64 v95, v95, v196, s[36:37]
	v_cndmask_b32_e64 v94, v94, v196, s[34:35]
	v_cndmask_b32_e64 v93, v93, v196, s[30:31]
	v_cndmask_b32_e64 v92, v92, v196, s[28:29]
	v_cndmask_b32_e64 v91, v91, v196, s[26:27]
	v_cndmask_b32_e64 v90, v90, v196, s[24:25]
	v_cndmask_b32_e64 v89, v89, v196, s[22:23]
	v_cndmask_b32_e64 v88, v88, v196, s[20:21]
	v_cndmask_b32_e64 v87, v87, v196, s[18:19]
	v_cndmask_b32_e64 v86, v86, v196, s[16:17]
	v_cndmask_b32_e64 v85, v85, v196, s[14:15]
	v_cndmask_b32_e64 v84, v84, v196, s[12:13]
	v_cndmask_b32_e64 v83, v83, v196, s[6:7]
	v_cndmask_b32_e64 v82, v82, v196, s[4:5]
	v_cndmask_b32_e64 v81, v81, v196, s[0:1]
	v_cndmask_b32_e32 v80, v80, v196, vcc
	s_branch .Latta_u2_478
.LBB0_482:
	s_waitcnt vmcnt(0) lgkmcnt(0)
	s_barrier
	v_cndmask_b32_e64 v64, 0, 1, s[64:65]
	v_cmp_ne_u32_e64 s[4:5], 1, v64
	s_andn2_b64 vcc, exec, s[64:65]
	v_lshl_add_u32 v67, v181, 2, s11
	s_cbranch_vccnz .LBB0_484
	ds_write2st64_b32 v67, v48, v49 offset1:1
	ds_write2st64_b32 v67, v50, v51 offset0:2 offset1:3
	ds_write2st64_b32 v67, v52, v53 offset0:4 offset1:5
	ds_write2st64_b32 v67, v54, v55 offset0:6 offset1:7
	ds_write2st64_b32 v67, v56, v57 offset0:8 offset1:9
	ds_write2st64_b32 v67, v58, v59 offset0:10 offset1:11
	ds_write2st64_b32 v67, v60, v61 offset0:12 offset1:13
	ds_write2st64_b32 v67, v62, v63 offset0:14 offset1:15
	ds_write2st64_b32 v67, v32, v33 offset0:16 offset1:17
	ds_write2st64_b32 v67, v34, v35 offset0:18 offset1:19
	ds_write2st64_b32 v67, v36, v37 offset0:20 offset1:21
	ds_write2st64_b32 v67, v38, v39 offset0:22 offset1:23
	ds_write2st64_b32 v67, v40, v41 offset0:24 offset1:25
	ds_write2st64_b32 v67, v42, v43 offset0:26 offset1:27
	ds_write2st64_b32 v67, v44, v45 offset0:28 offset1:29
	ds_write2st64_b32 v67, v46, v47 offset0:30 offset1:31
	ds_write2st64_b32 v67, v16, v17 offset0:32 offset1:33
	ds_write2st64_b32 v67, v18, v19 offset0:34 offset1:35
	ds_write2st64_b32 v67, v20, v21 offset0:36 offset1:37
	ds_write2st64_b32 v67, v22, v23 offset0:38 offset1:39
	ds_write2st64_b32 v67, v24, v25 offset0:40 offset1:41
	ds_write2st64_b32 v67, v26, v27 offset0:42 offset1:43
	ds_write2st64_b32 v67, v28, v29 offset0:44 offset1:45
	ds_write2st64_b32 v67, v30, v31 offset0:46 offset1:47
	ds_write2st64_b32 v67, v0, v1 offset0:48 offset1:49
	ds_write2st64_b32 v67, v2, v3 offset0:50 offset1:51
	ds_write2st64_b32 v67, v4, v5 offset0:52 offset1:53
	ds_write2st64_b32 v67, v6, v7 offset0:54 offset1:55
	ds_write2st64_b32 v67, v8, v9 offset0:56 offset1:57
	ds_write2st64_b32 v67, v10, v11 offset0:58 offset1:59
	ds_write2st64_b32 v67, v12, v13 offset0:60 offset1:61
	ds_write2st64_b32 v67, v14, v15 offset0:62 offset1:63
	ds_write2st64_b32 v67, v204, v190 offset0:64 offset1:65

; #define ATT_ISSUE_K(jt, stage) do { _Pragma("unroll") for (int i_ = 0; i_ < 3; ++i_) ATT_DMA(kg + (size_t)(jt) * KTILE + kgo[i_], KRING + (stage) * KTILE + (wave * 3 + i_) * 1024); } while (0)
; #define ATT_ISSUE_V(jt, stage) do { _Pragma("unroll") for (int i_ = 0; i_ < 2; ++i_) ATT_DMA(vg + (size_t)(jt) * 128 + vgo[i_], VRING + (stage) * VTILE + (wave * 2 + i_) * 1024); } while (0)
; __device__ __forceinline__ void attn_unit(LAS unsigned char* lds, const bf16_t* Qg, const bf16_t* Kg, const bf16_t* Vtg, bf16_t* Og, int bh, int qb, int tid_, int wave, int lane_) {
;     ...
;     const int rg = wave & 3, kh = wave >> 2, r = lane & 31, hi = lane >> 5;
;     const int b = bh >> 2, h = bh & 3;
;     const int nt = 2 * (qb + 1);
;     const float NEG = -1e30f;
;     bf16x8 qf[12];
;     { const bf16_t* qp = Qg + ((size_t)bh * SEQ + 128 * qb + 32 * rg + r) * QKD + 8 * hi;
; #pragma unroll
;       for (int kk = 0; kk < 12; ++kk) qf[kk] = *(const bf16x8*)(qp + 16 * kk); }
;     const unsigned char* kg = (const unsigned char*)(Kg + (size_t)bh * SEQ * QKD);
;     const unsigned char* vg = (const unsigned char*)(Vtg + (size_t)bh * VD * SEQ);
;     unsigned kgo[3], vgo[2];
; #pragma unroll
;     for (int i = 0; i < 3; ++i) { const int a = (wave * 3 + i) * 1024 + lane * 16, row = a / 384, cp = (a % 384) >> 4, cl = (cp & ~7) | ((cp ^ (row >> 1)) & 7); kgo[i] = (unsigned)(row * 384 + cl * 16); }
; #pragma unroll
;     for (int i = 0; i < 2; ++i) { const int a = (wave * 2 + i) * 1024 + lane * 16, row = a >> 7, cp = (a & 127) >> 4, cl = (cp ^ (row >> 1)) & 7; vgo[i] = (unsigned)(row * (SEQ * 2) + cl * 16); }
;     const int sw = (r >> 1) & 7;
;     unsigned kro[4], vro[2];
; #pragma unroll
;     for (int q = 0; q < 4; ++q) kro[q] = (unsigned)((32 * kh + r) * 384 + (((2 * q + hi) ^ sw) * 16));
; #pragma unroll
;     for (int s = 0; s < 2; ++s) vro[s] = (unsigned)(VRING + r * 128 + (((4 * kh + 2 * s + hi) ^ sw) * 16));
;     f32x16 o[4]; float mrun = NEG, lrun = 0.f;
; #pragma unroll
;     for (int dt = 0; dt < 4; ++dt)
; #pragma unroll
;         for (int i = 0; i < 16; ++i) o[dt][i] = 0.f;
;     ATT_ISSUE_K(0, 0); ATT_ISSUE_V(0, 0); ATT_ISSUE_K(1, 1);
;     ATT_ISSUE_K((2 < nt) ? 2 : nt - 1, 2); ATT_ISSUE_V(1, 1);
;     asm volatile("s_waitcnt vmcnt(5)" ::: "memory"); __builtin_amdgcn_s_barrier(); asm volatile("" ::: "memory");
.LBB0_486:
	s_lshl_b32 s52, s40, 1
	s_ashr_i32 s51, s50, 31
	v_mov_b32_e32 v6, v254
	s_add_u32 s0, s41, s50
	s_barrier
	s_addc_u32 s12, 0, s51
	v_and_b32_e32 v191, 31, v6
	s_or_b32 s0, s0, s97
	v_or_b32_e32 v2, s0, v191
	v_readlane_b32 s0, v255, 36
	v_readlane_b32 s1, v255, 37
	v_bfe_u32 v190, v6, 5, 1
	v_lshlrev_b32_e32 v176, 4, v190
	v_mov_b64_e32 v[0:1], s[0:1]
	v_mad_u64_u32 v[0:1], s[0:1], v2, s61, v[0:1]
	v_mad_i32_i24 v1, s12, v195, v1
	v_and_b32_e32 v181, 63, v6
	v_lshl_add_u64 v[0:1], v[0:1], 0, v[176:177]
	global_load_dwordx4 v[96:99], v[0:1], off
	global_load_dwordx4 v[100:103], v[0:1], off offset:32
	global_load_dwordx4 v[104:107], v[0:1], off offset:64
	global_load_dwordx4 v[108:111], v[0:1], off offset:96
	global_load_dwordx4 v[112:115], v[0:1], off offset:128
	global_load_dwordx4 v[116:119], v[0:1], off offset:160
	global_load_dwordx4 v[120:123], v[0:1], off offset:192
	global_load_dwordx4 v[124:127], v[0:1], off offset:224
	global_load_dwordx4 v[128:131], v[0:1], off offset:256
	global_load_dwordx4 v[132:135], v[0:1], off offset:288
	global_load_dwordx4 v[136:139], v[0:1], off offset:320
	global_load_dwordx4 v[140:143], v[0:1], off offset:352
	v_lshlrev_b32_e32 v0, 4, v181
	v_or_b32_e32 v1, s59, v0
	v_mul_hi_i32 v2, v1, s42
	v_lshrrev_b32_e32 v3, 31, v2
	v_ashrrev_i32_e32 v2, 6, v2
	v_add_u32_e32 v2, v2, v3
	v_mul_i32_i24_e32 v3, 0x180, v2
	v_lshlrev_b32_e32 v2, 3, v2
	v_sub_u32_e32 v1, v1, v3
	v_and_b32_e32 v2, 0x70, v2
	v_xad_u32 v182, v2, v1, v3
	v_or_b32_e32 v1, s60, v0
	v_mul_hi_i32 v2, v1, s42
	v_lshrrev_b32_e32 v3, 31, v2
	v_ashrrev_i32_e32 v2, 6, v2
	v_add_u32_e32 v2, v2, v3
	v_mul_i32_i24_e32 v3, 0x180, v2
	v_lshlrev_b32_e32 v2, 3, v2
	v_sub_u32_e32 v1, v1, v3
	v_and_b32_e32 v2, 0x70, v2
	v_xad_u32 v184, v2, v1, v3
	v_or_b32_e32 v1, s67, v0
	v_mul_hi_i32 v2, v1, s42
	v_lshrrev_b32_e32 v3, 31, v2
	v_ashrrev_i32_e32 v2, 6, v2
	v_add_u32_e32 v2, v2, v3
	v_mul_i32_i24_e32 v3, 0x180, v2
	v_lshlrev_b32_e32 v2, 3, v2
	v_sub_u32_e32 v1, v1, v3
	v_and_b32_e32 v2, 0x70, v2
	v_xad_u32 v186, v2, v1, v3
	v_or_b32_e32 v0, s68, v0
	v_lshlrev_b32_e32 v2, 4, v6
	v_and_b32_e32 v3, 48, v6
	s_mov_b32 m0, s71
	v_lshlrev_b32_e32 v1, 7, v0
	v_bitop3_b32 v2, v2, v3, s86 bitop3:0x6c
	v_or_b32_e32 v0, 0x400, v0
	v_and_or_b32 v176, v1, s62, v2
	v_lshrrev_b32_e32 v1, 8, v0
	global_load_lds_dwordx4 v182, s[92:93]
	s_mov_b32 m0, s91
	v_xor_b32_e32 v1, v1, v6
	v_lshlrev_b32_e32 v0, 7, v0
	global_load_lds_dwordx4 v184, s[92:93]
	s_mov_b32 m0, s74
	v_and_b32_e32 v0, 0xffffc000, v0
	v_lshlrev_b32_e32 v1, 4, v1
	global_load_lds_dwordx4 v186, s[92:93]
	s_mov_b32 m0, s96
	s_or_b32 s44, s52, 1
	v_and_or_b32 v188, v1, s86, v0
	global_load_lds_dwordx4 v176, s[94:95]
	s_mov_b32 m0, s43
	s_cmp_lt_i32 s40, 1
	global_load_lds_dwordx4 v188, s[94:95]
	s_mov_b32 m0, s75
	s_cselect_b32 s0, s44, 2
	global_load_lds_dwordx4 v182, s[38:39]
	s_mov_b32 m0, s90
	s_mul_hi_i32 s1, s0, 0x6000
	s_mulk_i32 s0, 0x6000
	global_load_lds_dwordx4 v184, s[38:39]
	s_mov_b32 m0, s2
	s_add_u32 s0, s92, s0
	global_load_lds_dwordx4 v186, s[38:39]
	s_addc_u32 s1, s93, s1
	s_mov_b32 m0, s85
	v_lshl_add_u64 v[0:1], s[94:95], 0, v[176:177]
	global_load_lds_dwordx4 v182, s[0:1]
	s_mov_b32 m0, s87
	v_mov_b32_e32 v189, v177
	global_load_lds_dwordx4 v184, s[0:1]
	s_mov_b32 m0, s3
	v_lshl_add_u64 v[2:3], s[94:95], 0, v[188:189]
	global_load_lds_dwordx4 v186, s[0:1]
	v_lshl_add_u64 v[0:1], v[0:1], 0, s[78:79]
	s_mov_b32 m0, s33
	s_nop 0
	global_load_lds_dwordx4 v[0:1], off
	v_lshl_add_u64 v[0:1], v[2:3], 0, s[78:79]
	s_mov_b32 m0, s10
	s_nop 0
	global_load_lds_dwordx4 v[0:1], off
	v_lshrrev_b32_e32 v0, 1, v6
	v_or_b32_e32 v1, s69, v191
	v_mul_lo_u32 v1, v1, s61
	v_bitop3_b32 v0, v190, v0, 7 bitop3:0x78
	v_lshl_or_b32 v199, v0, 4, v1
	s_waitcnt vmcnt(5)
	s_barrier
; #define LAS __attribute__((address_space(3)))
; #define MFMA32(a, b, c) __builtin_amdgcn_mfma_f32_32x32x16_bf16((a), (b), (c), 0, 0, 0)
; __device__ __forceinline__ void attn_unit(LAS unsigned char* lds, const bf16_t* Qg, const bf16_t* Kg, const bf16_t* Vtg, bf16_t* Og, int bh, int qb, int tid_, int wave, int lane_) {
;     ...
;     {
; #pragma unroll
;       for (int i = 0; i < 16; ++i) sc[i] = 0.f;
; #pragma unroll
;       for (int kk = 0; kk < 12; ++kk) { const bf16x8 kf = *(const LAS bf16x8*)(lds + KRING + kro[kk & 3] + (kk >> 2) * 128); sc = MFMA32(kf, qf[kk], sc); if ((kk & 3) == 3) __builtin_amdgcn_sched_barrier(0); } }
;     asm volatile("s_waitcnt lgkmcnt(0)" ::: "memory"); __builtin_amdgcn_s_barrier(); asm volatile("" ::: "memory");
;     const float NINF = -__builtin_inff();
;     int s0 = 0, s1 = 1, s2 = 2;
;     for (int j = 0; j < nt; ++j) {
;         const int relc = 64 * (j - 2 * qb) + 32 * kh - 32 * rg;
;         const int j3 = (j + 3 < nt) ? j + 3 : nt - 1, j2 = (j + 2 < nt) ? j + 2 : nt - 1;
;         const LAS unsigned char* kb = lds + KRING + s1 * KTILE;
;         const LAS unsigned char* vb = lds + s0 * VTILE;
;         if (relc >= 0) {
;             const int thr = (relc == 0) ? r : -1;
; #pragma unroll
;             for (int i = 0; i < 16; ++i) { const int key = (i & 3) + 8 * (i >> 2) + 4 * hi; if (key > thr) sc[i] = NINF; }
;         }
	v_add_u32_e32 v10, 0, v199
	ds_read_b128 v[2:5], v10
	v_bfe_u32 v0, v6, 1, 3
	v_bitop3_b32 v6, v190, v0, 2 bitop3:0x36
	v_lshl_or_b32 v200, v6, 4, v1
	v_add_u32_e32 v11, 0, v200
	ds_read_b128 v[6:9], v11
	s_waitcnt lgkmcnt(0)
	v_mfma_f32_32x32x16_bf16 v[64:79], v[2:5], v[96:99], 0
	v_bitop3_b32 v2, v190, v0, 4 bitop3:0x36
	v_lshl_or_b32 v201, v2, 4, v1
	v_add_u32_e32 v12, 0, v201
	ds_read_b128 v[2:5], v12
	v_mfma_f32_32x32x16_bf16 v[64:79], v[6:9], v[100:103], v[64:79]
	v_bitop3_b32 v6, v190, v0, 6 bitop3:0x36
	v_lshl_or_b32 v202, v6, 4, v1
	v_add_u32_e32 v1, 0, v202
	ds_read_b128 v[6:9], v1
	s_waitcnt lgkmcnt(1)
	v_mfma_f32_32x32x16_bf16 v[64:79], v[2:5], v[104:107], v[64:79]
	s_waitcnt lgkmcnt(0)
	v_mfma_f32_32x32x16_bf16 v[64:79], v[6:9], v[108:111], v[64:79]
	ds_read_b128 v[2:5], v10 offset:128
	ds_read_b128 v[6:9], v11 offset:128
	s_waitcnt lgkmcnt(1)
	v_mfma_f32_32x32x16_bf16 v[64:79], v[2:5], v[112:115], v[64:79]
	s_waitcnt lgkmcnt(0)
	v_mfma_f32_32x32x16_bf16 v[64:79], v[6:9], v[116:119], v[64:79]
	ds_read_b128 v[2:5], v12 offset:128
	ds_read_b128 v[6:9], v1 offset:128
	s_waitcnt lgkmcnt(1)
	v_mfma_f32_32x32x16_bf16 v[64:79], v[2:5], v[120:123], v[64:79]
	s_waitcnt lgkmcnt(0)
	v_mfma_f32_32x32x16_bf16 v[64:79], v[6:9], v[124:127], v[64:79]
	ds_read_b128 v[2:5], v10 offset:256
	ds_read_b128 v[6:9], v11 offset:256
	s_waitcnt lgkmcnt(1)
	v_mfma_f32_32x32x16_bf16 v[64:79], v[2:5], v[128:131], v[64:79]
	s_waitcnt lgkmcnt(0)
	v_mfma_f32_32x32x16_bf16 v[64:79], v[6:9], v[132:135], v[64:79]
	ds_read_b128 v[2:5], v12 offset:256
	ds_read_b128 v[6:9], v1 offset:256
	s_waitcnt lgkmcnt(1)
	v_mfma_f32_32x32x16_bf16 v[64:79], v[2:5], v[136:139], v[64:79]
	s_waitcnt lgkmcnt(0)
	v_mfma_f32_32x32x16_bf16 v[80:95], v[6:9], v[140:143], v[64:79]
	s_waitcnt lgkmcnt(0)
	s_barrier
	s_cmp_lt_i32 s40, 0
	s_cbranch_scc1 .LBB0_494
	v_or_b32_e32 v1, s70, v190
	v_bitop3_b32 v2, v190, v0, s70 bitop3:0x36
	v_bitop3_b32 v0, v1, v0, 2 bitop3:0x36
	v_mov_b32_e32 v14, v177
	v_mov_b32_e32 v15, v177
	v_lshlrev_b32_e32 v203, 4, v2
	v_lshlrev_b32_e32 v204, 4, v0
	v_mov_b32_e32 v0, v177
	v_mov_b32_e32 v1, v177
	v_mov_b32_e32 v2, v177
	v_mov_b32_e32 v3, v177
	v_mov_b32_e32 v4, v177
	v_mov_b32_e32 v5, v177
	v_mov_b32_e32 v6, v177
	v_mov_b32_e32 v7, v177
	v_mov_b32_e32 v8, v177
	v_mov_b32_e32 v9, v177
	v_mov_b32_e32 v10, v177
	v_mov_b32_e32 v11, v177
	v_mov_b32_e32 v12, v177
	v_mov_b32_e32 v13, v177
	v_mov_b64_e32 v[30:31], v[14:15]
	v_mov_b64_e32 v[46:47], v[14:15]
	v_mov_b64_e32 v[62:63], v[14:15]
	v_mov_b32_e32 v183, v177
	v_mov_b32_e32 v185, v177
	v_mov_b32_e32 v187, v177
	s_mov_b32 s53, 2
	s_add_i32 s45, s52, 2
	v_lshlrev_b32_e32 v205, 2, v190
	v_lshl_add_u32 v206, v191, 7, 0
	s_mov_b32 s32, 0x12000
	v_add3_u32 v225, v206, v203, s32
	v_add3_u32 v245, v206, v204, s32
	s_sub_i32 s54, s69, s50
	s_mov_b32 s0, 0
	s_mov_b32 s55, 1
	v_mov_b32_e32 v198, 0xf149f2ca
	v_mov_b32_e32 v226, 0
	v_mov_b32_e32 v227, v226
	v_mov_b32_e32 v228, v226
	v_mov_b32_e32 v229, v226
	v_mov_b32_e32 v230, v226
	v_mov_b32_e32 v231, v226
	v_mov_b32_e32 v232, v226
	v_mov_b32_e32 v233, v226
	v_mov_b32_e32 v234, v226
	v_mov_b32_e32 v235, v226
	v_mov_b32_e32 v236, v226
	v_mov_b32_e32 v237, v226
	v_mov_b32_e32 v238, v226
	v_mov_b32_e32 v239, v226
	v_mov_b32_e32 v240, v226
	v_mov_b32_e32 v241, v226
	v_mov_b32_e32 v242, 0xff7fffff
	v_mov_b32_e32 v243, 0
	v_mov_b32_e32 v180, 0
	v_readlane_b32 s56, v255, 55
	v_mov_b64_e32 v[28:29], v[12:13]
	v_mov_b64_e32 v[26:27], v[10:11]
	v_mov_b64_e32 v[24:25], v[8:9]
	v_mov_b64_e32 v[22:23], v[6:7]
	v_mov_b64_e32 v[20:21], v[4:5]
	v_mov_b64_e32 v[18:19], v[2:3]
	v_mov_b64_e32 v[16:17], v[0:1]
	v_mov_b64_e32 v[44:45], v[12:13]
	v_mov_b64_e32 v[42:43], v[10:11]
	v_mov_b64_e32 v[40:41], v[8:9]
	v_mov_b64_e32 v[38:39], v[6:7]
	v_mov_b64_e32 v[36:37], v[4:5]
	v_mov_b64_e32 v[34:35], v[2:3]
	v_mov_b64_e32 v[32:33], v[0:1]
	v_mov_b64_e32 v[60:61], v[12:13]
	v_mov_b64_e32 v[58:59], v[10:11]
	v_mov_b64_e32 v[56:57], v[8:9]
	v_mov_b64_e32 v[54:55], v[6:7]
	v_mov_b64_e32 v[52:53], v[4:5]
	v_mov_b64_e32 v[50:51], v[2:3]
	v_mov_b64_e32 v[48:49], v[0:1]
	s_mov_b32 s57, 0
	s_mov_b64 s[88:89], s[8:9]
	s_add_i32 s1, s54, s56
	s_cmp_lt_i32 s1, 0
	s_mov_b32 s58, s0
	s_cbranch_scc1 .LBB0_489
	s_branch .LBB0_488

; #define LAS __attribute__((address_space(3)))
; __device__ __forceinline__ void attn_unit(LAS unsigned char* lds, const bf16_t* Qg, const bf16_t* Kg, const bf16_t* Vtg, bf16_t* Og, int bh, int qb, int tid_, int wave, int lane_) {
;     ...
;         if (__builtin_amdgcn_ballot_w64(mx > mrun + 8.f) != 0ull) {
;             const float mnew = fmaxf(mrun, mx); const float alpha = __builtin_amdgcn_exp2f(mrun - mnew); mrun = mnew; lrun *= alpha;
; #pragma unroll
;             for (int dt = 0; dt < 4; ++dt) o[dt] = o[dt] * alpha;
;         }
;         float ps = 0.f; u32x4 p0, p1;
; #pragma unroll
;         for (int q = 0; q < 4; ++q) sn = MFMA32(fb[q], qf[4 + q], sn);
; #pragma unroll
;         for (int i = 0; i < 8; ++i) { sc[i] = __builtin_amdgcn_exp2f(sc[i] - mrun); ps += sc[i]; }
;         p0.x = pk2(sc[0], sc[1]); p0.y = pk2(sc[2], sc[3]); p0.z = pk2(sc[4], sc[5]); p0.w = pk2(sc[6], sc[7]);
;         __builtin_amdgcn_sched_barrier(0);
; #pragma unroll
;         for (int dt = 0; dt < 4; ++dt) fb[dt] = *(const LAS bf16x8*)(vb + vro[0] + dt * 4096);
;         __builtin_amdgcn_sched_barrier(0);
;         ATT_ISSUE_K(j3, s0);
;         __builtin_amdgcn_sched_barrier(0);
; #pragma unroll
;         for (int q = 0; q < 4; ++q) sn = MFMA32(fa[q], qf[8 + q], sn);
; #pragma unroll
;         for (int i = 8; i < 12; ++i) { sc[i] = __builtin_amdgcn_exp2f(sc[i] - mrun); ps += sc[i]; }
;         p1.x = pk2(sc[8], sc[9]); p1.y = pk2(sc[10], sc[11]);
;         __builtin_amdgcn_sched_barrier(0);
;         ATT_ISSUE_V(j2, s2);
;         __builtin_amdgcn_sched_barrier(0);
; #pragma unroll
;         for (int dt = 0; dt < 4; ++dt) fa[dt] = *(const LAS bf16x8*)(vb + vro[1] + dt * 4096);
;         { const bf16x8 pf0 = __builtin_bit_cast(bf16x8, p0);
;           o[0] = MFMA32(fb[0], pf0, o[0]); o[1] = MFMA32(fb[1], pf0, o[1]); o[2] = MFMA32(fb[2], pf0, o[2]); o[3] = MFMA32(fb[3], pf0, o[3]); }
; #pragma unroll
;         for (int i = 12; i < 16; ++i) { sc[i] = __builtin_amdgcn_exp2f(sc[i] - mrun); ps += sc[i]; }
;         p1.z = pk2(sc[12], sc[13]); p1.w = pk2(sc[14], sc[15]);
;         lrun += ps;
;         __builtin_amdgcn_sched_barrier(0);
;         { const bf16x8 pf1 = __builtin_bit_cast(bf16x8, p1);
;           o[0] = MFMA32(fa[0], pf1, o[0]); o[1] = MFMA32(fa[1], pf1, o[1]); o[2] = MFMA32(fa[2], pf1, o[2]); o[3] = MFMA32(fa[3], pf1, o[3]); }
.LBB0_492:
	v_mfma_f32_32x32x16_bf16 v[64:79], v[164:167], v[112:115], v[64:79]
	v_exp_f32_e32 v192, v80
	v_exp_f32_e32 v193, v81
	v_exp_f32_e32 v194, v82
	s_waitcnt lgkmcnt(0)
	v_mfma_f32_32x32x16_bf16 v[64:79], v[172:175], v[116:119], v[64:79]
	v_exp_f32_e32 v207, v83
	v_exp_f32_e32 v208, v84
	v_exp_f32_e32 v209, v85
	v_exp_f32_e32 v210, v86
	v_mfma_f32_32x32x16_bf16 v[64:79], v[168:171], v[120:123], v[64:79]
	s_add_i32 s0, s57, 3
	v_exp_f32_e32 v211, v87
	s_cmp_lt_i32 s0, s45
	s_cselect_b32 s0, s0, s44
	s_add_i32 s1, s57, 2
	s_cmp_lt_i32 s57, s52
	s_cselect_b32 s48, s1, s44
	v_cvt_pk_bf16_f32 v246, v192, v193
	v_cvt_pk_bf16_f32 v247, v194, v207
	v_cvt_pk_bf16_f32 v248, v208, v209
	v_cvt_pk_bf16_f32 v249, v210, v211
	ds_read_b128 v[214:217], v225
	ds_read_b128 v[164:167], v225 offset:4096
	ds_read_b128 v[168:171], v225 offset:8192
	ds_read_b128 v[172:175], v225 offset:12288
	v_add_f32_e32 v192, v193, v192
	v_add_f32_e32 v192, v194, v192
	v_add_f32_e32 v192, v207, v192
	v_add_f32_e32 v192, v208, v192
	v_add_f32_e32 v192, v209, v192
	v_add_f32_e32 v192, v210, v192
	v_add_f32_e32 v194, v211, v192
	s_mul_hi_u32 s1, s0, 0x6000
	s_mulk_i32 s0, 0x6000
	s_add_u32 s0, s92, s0
	s_mul_i32 s12, s58, 0x6000
	s_addc_u32 s1, s93, s1
	s_add_i32 s12, s71, s12
	s_mov_b32 m0, s12
	s_waitcnt lgkmcnt(5)
	v_mfma_f32_32x32x16_bf16 v[64:79], v[160:163], v[124:127], v[64:79]
	global_load_lds_dwordx4 v182, s[0:1]
	s_add_i32 m0, s12, 0x400
	s_nop 0
	global_load_lds_dwordx4 v184, s[0:1]
	s_add_i32 m0, s12, 0x800
	s_nop 0
	global_load_lds_dwordx4 v186, s[0:1]
	v_mfma_f32_32x32x16_bf16 v[64:79], v[148:151], v[128:131], v[64:79]
	v_exp_f32_e32 v220, v88
	v_exp_f32_e32 v221, v89
	v_exp_f32_e32 v222, v90
	v_mfma_f32_32x32x16_bf16 v[64:79], v[156:159], v[132:135], v[64:79]
	v_exp_f32_e32 v223, v91
	v_add_f32_e32 v148, v220, v194
	v_add_f32_e32 v148, v221, v148
	v_add_f32_e32 v148, v222, v148
	v_add_f32_e32 v156, v223, v148
	v_cvt_pk_bf16_f32 v250, v220, v221
	v_cvt_pk_bf16_f32 v251, v222, v223
	v_mfma_f32_32x32x16_bf16 v[64:79], v[152:155], v[136:139], v[64:79]
	v_exp_f32_e32 v220, v92
	v_exp_f32_e32 v221, v93
	v_exp_f32_e32 v222, v94
	v_exp_f32_e32 v223, v95
	s_waitcnt lgkmcnt(0)
	v_mfma_f32_32x32x16_bf16 v[80:95], v[144:147], v[140:143], v[64:79]
	s_lshl_b64 s[0:1], s[48:49], 7
	s_add_u32 s0, s94, s0
	s_addc_u32 s1, s95, s1
	s_lshl_b32 s12, s53, 14
	s_add_i32 s12, s12, 0
	s_add_i32 s12, s12, s68
	s_add_i32 m0, s12, 0x12000
	s_nop 0
	global_load_lds_dwordx4 v176, s[0:1]
	s_add_i32 m0, s12, 0x12400
	s_nop 0
	global_load_lds_dwordx4 v188, s[0:1]
	v_mfma_f32_32x32x16_bf16 v[48:63], v[214:217], v[246:249], v[48:63]
	ds_read_b128 v[214:217], v245
	ds_read_b128 v[144:147], v245 offset:4096
	ds_read_b128 v[148:151], v245 offset:8192
	ds_read_b128 v[152:155], v245 offset:12288
	v_mfma_f32_32x32x16_bf16 v[32:47], v[164:167], v[246:249], v[32:47]
	v_add_f32_e32 v213, v220, v156
	v_add_f32_e32 v213, v221, v213
	v_add_f32_e32 v213, v222, v213
	v_add_f32_e32 v213, v223, v213
	v_add_f32_e32 v180, v180, v213
	v_mfma_f32_32x32x16_bf16 v[16:31], v[168:171], v[246:249], v[16:31]
	v_cvt_pk_bf16_f32 v252, v220, v221
	v_cvt_pk_bf16_f32 v253, v222, v223
	v_mfma_f32_32x32x16_bf16 v[0:15], v[172:175], v[246:249], v[0:15]
	s_waitcnt lgkmcnt(0)
	v_mfma_f32_32x32x16_bf16 v[48:63], v[214:217], v[250:253], v[48:63]
	s_waitcnt vmcnt(5) lgkmcnt(0)
	s_barrier
	s_add_i32 s57, s57, 1
	s_add_i32 s56, s56, 64
	s_cmp_eq_u32 s45, s57
	v_mfma_f32_32x32x16_bf16 v[32:47], v[144:147], v[250:253], v[32:47]
	v_mfma_f32_32x32x16_bf16 v[16:31], v[148:151], v[250:253], v[16:31]
	v_mfma_f32_32x32x16_bf16 v[0:15], v[152:155], v[250:253], v[0:15]
	s_cbranch_scc1 .LBB0_495
	s_mov_b32 s0, s55
	s_mov_b32 s55, s53
	s_mov_b32 s53, s58
	s_add_i32 s1, s54, s56
	s_cmp_lt_i32 s1, 0
	s_mov_b32 s58, s0
	s_cbranch_scc0 .Lattb_u1_488
.Lattb_u1_489:
.Lattb_u1_490:
	ds_read_b128 v[64:67], v199 offset:49152
	ds_read_b128 v[144:147], v200 offset:49152
	ds_read_b128 v[208:211], v202 offset:49152
	ds_read_b128 v[164:167], v199 offset:49280
	ds_read_b128 v[152:155], v201 offset:49152
	ds_read_b128 v[168:171], v201 offset:49280
	s_waitcnt lgkmcnt(0)
	v_mfma_f32_32x32x16_bf16 v[64:79], v[64:67], v[96:99], v[226:241]
	v_max_f32_e32 v149, v80, v81
	v_max3_f32 v157, v149, v82, v83
	ds_read_b128 v[148:151], v199 offset:49408
	s_waitcnt lgkmcnt(5)
	v_mfma_f32_32x32x16_bf16 v[64:79], v[144:147], v[100:103], v[64:79]
	v_max3_f32 v144, v157, v84, v85
	v_max3_f32 v144, v144, v86, v87
	v_max3_f32 v144, v144, v88, v89
	v_max3_f32 v144, v144, v90, v91
	v_max3_f32 v144, v144, v92, v93
	v_max3_f32 v193, v144, v94, v95
	s_waitcnt lgkmcnt(2)
	v_mfma_f32_32x32x16_bf16 v[64:79], v[152:155], v[104:107], v[64:79]
	ds_read_b128 v[172:175], v200 offset:49280
	ds_read_b128 v[156:159], v200 offset:49408
	ds_read_b128 v[152:155], v201 offset:49408
	ds_read_b128 v[160:163], v202 offset:49280
	ds_read_b128 v[144:147], v202 offset:49408
	v_mfma_f32_32x32x16_bf16 v[64:79], v[208:211], v[108:111], v[64:79]
	v_cmp_gt_f32_e32 vcc, v193, v242
	s_cbranch_vccz .Lattb_u1_492
; __device__ __forceinline__ unsigned pk2(float a, float b) { f32x2_t v = {a, b}; bf16x2v_t r = __builtin_convertvector(v, bf16x2v_t); return __builtin_bit_cast(unsigned, r); }
; #define LAS __attribute__((address_space(3)))
; #define MFMA32(a, b, c) __builtin_amdgcn_mfma_f32_32x32x16_bf16((a), (b), (c), 0, 0, 0)
; #define ATT_ISSUE_K(jt, stage) do { _Pragma("unroll") for (int i_ = 0; i_ < 3; ++i_) ATT_DMA(kg + (size_t)(jt) * KTILE + kgo[i_], KRING + (stage) * KTILE + (wave * 3 + i_) * 1024); } while (0)
; __device__ __forceinline__ void attn_unit(LAS unsigned char* lds, const bf16_t* Qg, const bf16_t* Kg, const bf16_t* Vtg, bf16_t* Og, int bh, int qb, int tid_, int wave, int lane_) {
;     ...
;             const float mnew = fmaxf(mrun, mx); const float alpha = __builtin_amdgcn_exp2f(mrun - mnew); mrun = mnew; lrun *= alpha;
; #pragma unroll
;             for (int dt = 0; dt < 4; ++dt) o[dt] = o[dt] * alpha;
;         }
;         float ps = 0.f; u32x4 p0, p1;
; #pragma unroll
;         for (int q = 0; q < 4; ++q) sn = MFMA32(fb[q], qf[4 + q], sn);
; #pragma unroll
;         for (int i = 0; i < 8; ++i) { sc[i] = __builtin_amdgcn_exp2f(sc[i] - mrun); ps += sc[i]; }
;         p0.x = pk2(sc[0], sc[1]); p0.y = pk2(sc[2], sc[3]); p0.z = pk2(sc[4], sc[5]); p0.w = pk2(sc[6], sc[7]);
;         __builtin_amdgcn_sched_barrier(0);
; #pragma unroll
;         for (int dt = 0; dt < 4; ++dt) fb[dt] = *(const LAS bf16x8*)(vb + vro[0] + dt * 4096);
;         __builtin_amdgcn_sched_barrier(0);
;         ATT_ISSUE_K(j3, s0);
;         __builtin_amdgcn_sched_barrier(0);
; #pragma unroll
;         for (int q = 0; q < 4; ++q) sn = MFMA32(fa[q], qf[8 + q], sn);
; #pragma unroll
;         for (int i = 8; i < 12; ++i) { sc[i] = __builtin_amdgcn_exp2f(sc[i] - mrun); ps += sc[i]; }
;         p1.x = pk2(sc[8], sc[9]); p1.y = pk2(sc[10], sc[11]);
	v_mov_b32_e32 v194, v193
	s_nop 1
	v_permlane32_swap_b32_e32 v193, v194
	v_max_f32_e32 v207, v193, v194
	v_add_f32_e32 v192, v207, v243
	v_max_f32_e32 v193, v198, v198
	v_max_f32_e32 v193, v193, v192
	v_sub_f32_e32 v192, v198, v193
	v_sub_f32_e32 v244, v243, v193
	v_exp_f32_e32 v192, v192
	v_mov_b32_e32 v198, v193
	v_mov_b32_e32 v243, v193
	v_mov_b32_e32 v242, 0x41000000
	v_pk_mul_f32 v[62:63], v[62:63], v[192:193] op_sel_hi:[1,0]
	v_pk_mul_f32 v[60:61], v[60:61], v[192:193] op_sel_hi:[1,0]
	v_pk_mul_f32 v[58:59], v[58:59], v[192:193] op_sel_hi:[1,0]
	v_pk_mul_f32 v[56:57], v[56:57], v[192:193] op_sel_hi:[1,0]
	v_pk_mul_f32 v[54:55], v[54:55], v[192:193] op_sel_hi:[1,0]
	v_pk_mul_f32 v[52:53], v[52:53], v[192:193] op_sel_hi:[1,0]
	v_pk_mul_f32 v[50:51], v[50:51], v[192:193] op_sel_hi:[1,0]
	v_pk_mul_f32 v[48:49], v[48:49], v[192:193] op_sel_hi:[1,0]
	v_pk_mul_f32 v[46:47], v[46:47], v[192:193] op_sel_hi:[1,0]
	v_pk_mul_f32 v[44:45], v[44:45], v[192:193] op_sel_hi:[1,0]
	v_pk_mul_f32 v[42:43], v[42:43], v[192:193] op_sel_hi:[1,0]
	v_pk_mul_f32 v[40:41], v[40:41], v[192:193] op_sel_hi:[1,0]
	v_pk_mul_f32 v[38:39], v[38:39], v[192:193] op_sel_hi:[1,0]
	v_pk_mul_f32 v[36:37], v[36:37], v[192:193] op_sel_hi:[1,0]
	v_pk_mul_f32 v[34:35], v[34:35], v[192:193] op_sel_hi:[1,0]
	v_pk_mul_f32 v[32:33], v[32:33], v[192:193] op_sel_hi:[1,0]
	v_pk_mul_f32 v[30:31], v[30:31], v[192:193] op_sel_hi:[1,0]
	v_pk_mul_f32 v[28:29], v[28:29], v[192:193] op_sel_hi:[1,0]
	v_pk_mul_f32 v[26:27], v[26:27], v[192:193] op_sel_hi:[1,0]
	v_pk_mul_f32 v[24:25], v[24:25], v[192:193] op_sel_hi:[1,0]
	v_pk_mul_f32 v[22:23], v[22:23], v[192:193] op_sel_hi:[1,0]
	v_pk_mul_f32 v[20:21], v[20:21], v[192:193] op_sel_hi:[1,0]
	v_pk_mul_f32 v[18:19], v[18:19], v[192:193] op_sel_hi:[1,0]
	v_pk_mul_f32 v[16:17], v[16:17], v[192:193] op_sel_hi:[1,0]
	v_pk_mul_f32 v[14:15], v[14:15], v[192:193] op_sel_hi:[1,0]
	v_pk_mul_f32 v[12:13], v[12:13], v[192:193] op_sel_hi:[1,0]
	v_pk_mul_f32 v[10:11], v[10:11], v[192:193] op_sel_hi:[1,0]
	v_pk_mul_f32 v[8:9], v[8:9], v[192:193] op_sel_hi:[1,0]
	v_pk_mul_f32 v[6:7], v[6:7], v[192:193] op_sel_hi:[1,0]
	v_pk_mul_f32 v[4:5], v[4:5], v[192:193] op_sel_hi:[1,0]
	v_pk_mul_f32 v[2:3], v[2:3], v[192:193] op_sel_hi:[1,0]
	v_pk_mul_f32 v[0:1], v[0:1], v[192:193] op_sel_hi:[1,0]
	v_mul_f32_e32 v180, v180, v192
	v_add_f32_e32 v80, v80, v244
	v_add_f32_e32 v81, v81, v244
	v_add_f32_e32 v82, v82, v244
	v_add_f32_e32 v83, v83, v244
	v_add_f32_e32 v84, v84, v244
	v_add_f32_e32 v85, v85, v244
	v_add_f32_e32 v86, v86, v244
	v_add_f32_e32 v87, v87, v244
	v_add_f32_e32 v88, v88, v244
	v_add_f32_e32 v89, v89, v244
	v_add_f32_e32 v90, v90, v244
	v_add_f32_e32 v91, v91, v244
	v_add_f32_e32 v92, v92, v244
	v_add_f32_e32 v93, v93, v244
	v_add_f32_e32 v94, v94, v244
	v_add_f32_e32 v95, v95, v244
	v_add_f32_e32 v64, v64, v244
	v_add_f32_e32 v65, v65, v244
	v_add_f32_e32 v66, v66, v244
	v_add_f32_e32 v67, v67, v244
	v_add_f32_e32 v68, v68, v244
	v_add_f32_e32 v69, v69, v244
	v_add_f32_e32 v70, v70, v244
	v_add_f32_e32 v71, v71, v244
	v_add_f32_e32 v72, v72, v244
	v_add_f32_e32 v73, v73, v244
	v_add_f32_e32 v74, v74, v244
	v_add_f32_e32 v75, v75, v244
	v_add_f32_e32 v76, v76, v244
	v_add_f32_e32 v77, v77, v244
	v_add_f32_e32 v78, v78, v244
	v_add_f32_e32 v79, v79, v244
	v_sub_f32_e32 v226, 0, v193
	v_mov_b32_e32 v227, v226
	v_mov_b32_e32 v228, v226
	v_mov_b32_e32 v229, v226
	v_mov_b32_e32 v230, v226
	v_mov_b32_e32 v231, v226
	v_mov_b32_e32 v232, v226
	v_mov_b32_e32 v233, v226
	v_mov_b32_e32 v234, v226
	v_mov_b32_e32 v235, v226
	v_mov_b32_e32 v236, v226
	v_mov_b32_e32 v237, v226
	v_mov_b32_e32 v238, v226
	v_mov_b32_e32 v239, v226
	v_mov_b32_e32 v240, v226
	v_mov_b32_e32 v241, v226
.Lattb_u1_492:
	v_mfma_f32_32x32x16_bf16 v[64:79], v[164:167], v[112:115], v[64:79]
	v_exp_f32_e32 v192, v80
	v_exp_f32_e32 v193, v81
	v_exp_f32_e32 v194, v82
	s_waitcnt lgkmcnt(0)
	v_mfma_f32_32x32x16_bf16 v[64:79], v[172:175], v[116:119], v[64:79]
	v_exp_f32_e32 v207, v83
	v_exp_f32_e32 v208, v84
	v_exp_f32_e32 v209, v85
	v_exp_f32_e32 v210, v86
	v_mfma_f32_32x32x16_bf16 v[64:79], v[168:171], v[120:123], v[64:79]
	s_add_i32 s0, s57, 3
	v_exp_f32_e32 v211, v87
	s_cmp_lt_i32 s0, s45
	s_cselect_b32 s0, s0, s44
	s_add_i32 s1, s57, 2
	s_cmp_lt_i32 s57, s52
	s_cselect_b32 s48, s1, s44
	v_cvt_pk_bf16_f32 v246, v192, v193
	v_cvt_pk_bf16_f32 v247, v194, v207
	v_cvt_pk_bf16_f32 v248, v208, v209
	v_cvt_pk_bf16_f32 v249, v210, v211
	ds_read_b128 v[214:217], v225 offset:16384
	ds_read_b128 v[164:167], v225 offset:20480
	ds_read_b128 v[168:171], v225 offset:24576
	ds_read_b128 v[172:175], v225 offset:28672
	v_add_f32_e32 v192, v193, v192
	v_add_f32_e32 v192, v194, v192
	v_add_f32_e32 v192, v207, v192
	v_add_f32_e32 v192, v208, v192
	v_add_f32_e32 v192, v209, v192
	v_add_f32_e32 v192, v210, v192
	v_add_f32_e32 v194, v211, v192
	s_mul_hi_u32 s1, s0, 0x6000
	s_mulk_i32 s0, 0x6000
	s_add_u32 s0, s92, s0
	s_mul_i32 s12, s58, 0x6000
	s_addc_u32 s1, s93, s1
	s_add_i32 s12, s71, s12
	s_mov_b32 m0, s12
	s_waitcnt lgkmcnt(5)
	v_mfma_f32_32x32x16_bf16 v[64:79], v[160:163], v[124:127], v[64:79]
	global_load_lds_dwordx4 v182, s[0:1]
	s_add_i32 m0, s12, 0x400
	s_nop 0
	global_load_lds_dwordx4 v184, s[0:1]
	s_add_i32 m0, s12, 0x800
	s_nop 0
	global_load_lds_dwordx4 v186, s[0:1]
	v_mfma_f32_32x32x16_bf16 v[64:79], v[148:151], v[128:131], v[64:79]
	v_exp_f32_e32 v220, v88
	v_exp_f32_e32 v221, v89
	v_exp_f32_e32 v222, v90
	v_mfma_f32_32x32x16_bf16 v[64:79], v[156:159], v[132:135], v[64:79]
	v_exp_f32_e32 v223, v91
	v_add_f32_e32 v148, v220, v194
	v_add_f32_e32 v148, v221, v148
	v_add_f32_e32 v148, v222, v148
	v_add_f32_e32 v156, v223, v148
	v_cvt_pk_bf16_f32 v250, v220, v221
	v_cvt_pk_bf16_f32 v251, v222, v223
	v_mfma_f32_32x32x16_bf16 v[64:79], v[152:155], v[136:139], v[64:79]
	v_exp_f32_e32 v220, v92
	v_exp_f32_e32 v221, v93
	v_exp_f32_e32 v222, v94
	v_exp_f32_e32 v223, v95
	s_waitcnt lgkmcnt(0)
; __device__ __forceinline__ void attn_unit(LAS unsigned char* lds, const bf16_t* Qg, const bf16_t* Kg, const bf16_t* Vtg, bf16_t* Og, int bh, int qb, int tid_, int wave, int lane_) {
;     ...
;     for (int j = 0; j < nt; ++j) {
;         const int relc = 64 * (j - 2 * qb) + 32 * kh - 32 * rg;
;         const int j3 = (j + 3 < nt) ? j + 3 : nt - 1, j2 = (j + 2 < nt) ? j + 2 : nt - 1;
;         const LAS unsigned char* kb = lds + KRING + s1 * KTILE;
;         const LAS unsigned char* vb = lds + s0 * VTILE;
;         if (relc >= 0) {
;             const int thr = (relc == 0) ? r : -1;
; #pragma unroll
;             for (int i = 0; i < 16; ++i) { const int key = (i & 3) + 8 * (i >> 2) + 4 * hi; if (key > thr) sc[i] = NINF; }
;         }
;     ...
;         bf16x8 fa[4], fb[4];
;         ATT_KRD(fa, 0); ATT_KRD(fb, 1);
; #pragma unroll
;         for (int i = 0; i < 16; ++i) sn[i] = 0.f;
;         float mx = sc[0];
; #pragma unroll
;         for (int i = 1; i < 16; ++i) mx = fmaxf(mx, sc[i]);
;         mx = max_xor32(mx);
; #pragma unroll
;         for (int q = 0; q < 4; ++q) sn = MFMA32(fa[q], qf[q], sn);
;         ATT_KRD(fa, 2);
;         __builtin_amdgcn_sched_barrier(0);
;         if (__builtin_amdgcn_ballot_w64(mx > mrun + 8.f) != 0ull) {
;     ...
;         __builtin_amdgcn_sched_barrier(0);
;         ATT_ISSUE_V(j2, s2);
;         __builtin_amdgcn_sched_barrier(0);
; #pragma unroll
;         for (int dt = 0; dt < 4; ++dt) fa[dt] = *(const LAS bf16x8*)(vb + vro[1] + dt * 4096);
;         { const bf16x8 pf0 = __builtin_bit_cast(bf16x8, p0);
;           o[0] = MFMA32(fb[0], pf0, o[0]); o[1] = MFMA32(fb[1], pf0, o[1]); o[2] = MFMA32(fb[2], pf0, o[2]); o[3] = MFMA32(fb[3], pf0, o[3]); }
; #pragma unroll
;         for (int i = 12; i < 16; ++i) { sc[i] = __builtin_amdgcn_exp2f(sc[i] - mrun); ps += sc[i]; }
;         p1.z = pk2(sc[12], sc[13]); p1.w = pk2(sc[14], sc[15]);
;         lrun += ps;
;         __builtin_amdgcn_sched_barrier(0);
;         { const bf16x8 pf1 = __builtin_bit_cast(bf16x8, p1);
;           o[0] = MFMA32(fa[0], pf1, o[0]); o[1] = MFMA32(fa[1], pf1, o[1]); o[2] = MFMA32(fa[2], pf1, o[2]); o[3] = MFMA32(fa[3], pf1, o[3]); }
;         asm volatile("s_waitcnt vmcnt(5) lgkmcnt(0)" ::: "memory"); __builtin_amdgcn_s_barrier(); asm volatile("" ::: "memory");
;         sc = sn;
;         { const int t = s0; s0 = s1; s1 = s2; s2 = t; }
;     }
	v_mfma_f32_32x32x16_bf16 v[80:95], v[144:147], v[140:143], v[64:79]
	s_lshl_b64 s[0:1], s[48:49], 7
	s_add_u32 s0, s94, s0
	s_addc_u32 s1, s95, s1
	s_lshl_b32 s12, s53, 14
	s_add_i32 s12, s12, 0
	s_add_i32 s12, s12, s68
	s_add_i32 m0, s12, 0x12000
	s_nop 0
	global_load_lds_dwordx4 v176, s[0:1]
	s_add_i32 m0, s12, 0x12400
	s_nop 0
	global_load_lds_dwordx4 v188, s[0:1]
	v_mfma_f32_32x32x16_bf16 v[48:63], v[214:217], v[246:249], v[48:63]
	ds_read_b128 v[214:217], v245 offset:16384
	ds_read_b128 v[144:147], v245 offset:20480
	ds_read_b128 v[148:151], v245 offset:24576
	ds_read_b128 v[152:155], v245 offset:28672
	v_mfma_f32_32x32x16_bf16 v[32:47], v[164:167], v[246:249], v[32:47]
	v_add_f32_e32 v213, v220, v156
	v_add_f32_e32 v213, v221, v213
	v_add_f32_e32 v213, v222, v213
	v_add_f32_e32 v213, v223, v213
	v_add_f32_e32 v180, v180, v213
	v_mfma_f32_32x32x16_bf16 v[16:31], v[168:171], v[246:249], v[16:31]
	v_cvt_pk_bf16_f32 v252, v220, v221
	v_cvt_pk_bf16_f32 v253, v222, v223
	v_mfma_f32_32x32x16_bf16 v[0:15], v[172:175], v[246:249], v[0:15]
	s_waitcnt lgkmcnt(0)
	v_mfma_f32_32x32x16_bf16 v[48:63], v[214:217], v[250:253], v[48:63]
	s_waitcnt vmcnt(5) lgkmcnt(0)
	s_barrier
	s_add_i32 s57, s57, 1
	s_add_i32 s56, s56, 64
	s_cmp_eq_u32 s45, s57
	v_mfma_f32_32x32x16_bf16 v[32:47], v[144:147], v[250:253], v[32:47]
	v_mfma_f32_32x32x16_bf16 v[16:31], v[148:151], v[250:253], v[16:31]
	v_mfma_f32_32x32x16_bf16 v[0:15], v[152:155], v[250:253], v[0:15]
	s_cbranch_scc1 .LBB0_495
	s_mov_b32 s0, s55
	s_mov_b32 s55, s53
	s_mov_b32 s53, s58
	s_add_i32 s1, s54, s56
	s_cmp_lt_i32 s1, 0
	s_mov_b32 s58, s0
	s_cbranch_scc0 .Lattb_u2_488
.Lattb_u2_489:
.Lattb_u2_490:
	ds_read_b128 v[64:67], v199
	ds_read_b128 v[144:147], v200
	ds_read_b128 v[208:211], v202
	ds_read_b128 v[164:167], v199 offset:128
	ds_read_b128 v[152:155], v201
	ds_read_b128 v[168:171], v201 offset:128
	s_waitcnt lgkmcnt(0)
	v_mfma_f32_32x32x16_bf16 v[64:79], v[64:67], v[96:99], v[226:241]
	v_max_f32_e32 v149, v80, v81
	v_max3_f32 v157, v149, v82, v83
	ds_read_b128 v[148:151], v199 offset:256
	s_waitcnt lgkmcnt(5)
	v_mfma_f32_32x32x16_bf16 v[64:79], v[144:147], v[100:103], v[64:79]
	v_max3_f32 v144, v157, v84, v85
	v_max3_f32 v144, v144, v86, v87
	v_max3_f32 v144, v144, v88, v89
	v_max3_f32 v144, v144, v90, v91
	v_max3_f32 v144, v144, v92, v93
	v_max3_f32 v193, v144, v94, v95
	s_waitcnt lgkmcnt(2)
	v_mfma_f32_32x32x16_bf16 v[64:79], v[152:155], v[104:107], v[64:79]
	ds_read_b128 v[172:175], v200 offset:128
	ds_read_b128 v[156:159], v200 offset:256
	ds_read_b128 v[152:155], v201 offset:256
	ds_read_b128 v[160:163], v202 offset:128
	ds_read_b128 v[144:147], v202 offset:256
	v_mfma_f32_32x32x16_bf16 v[64:79], v[208:211], v[108:111], v[64:79]
	v_cmp_gt_f32_e32 vcc, v193, v242
	s_cbranch_vccz .Lattb_u2_492
	v_mov_b32_e32 v194, v193
	s_nop 1
	v_permlane32_swap_b32_e32 v193, v194
	v_max_f32_e32 v207, v193, v194
	v_add_f32_e32 v192, v207, v243
	v_max_f32_e32 v193, v198, v198
	v_max_f32_e32 v193, v193, v192
	v_sub_f32_e32 v192, v198, v193
	v_sub_f32_e32 v244, v243, v193
	v_exp_f32_e32 v192, v192
	v_mov_b32_e32 v198, v193
	v_mov_b32_e32 v243, v193
	v_mov_b32_e32 v242, 0x41000000
	v_pk_mul_f32 v[62:63], v[62:63], v[192:193] op_sel_hi:[1,0]
	v_pk_mul_f32 v[60:61], v[60:61], v[192:193] op_sel_hi:[1,0]
	v_pk_mul_f32 v[58:59], v[58:59], v[192:193] op_sel_hi:[1,0]
	v_pk_mul_f32 v[56:57], v[56:57], v[192:193] op_sel_hi:[1,0]
	v_pk_mul_f32 v[54:55], v[54:55], v[192:193] op_sel_hi:[1,0]
	v_pk_mul_f32 v[52:53], v[52:53], v[192:193] op_sel_hi:[1,0]
	v_pk_mul_f32 v[50:51], v[50:51], v[192:193] op_sel_hi:[1,0]
	v_pk_mul_f32 v[48:49], v[48:49], v[192:193] op_sel_hi:[1,0]
	v_pk_mul_f32 v[46:47], v[46:47], v[192:193] op_sel_hi:[1,0]
	v_pk_mul_f32 v[44:45], v[44:45], v[192:193] op_sel_hi:[1,0]
	v_pk_mul_f32 v[42:43], v[42:43], v[192:193] op_sel_hi:[1,0]
	v_pk_mul_f32 v[40:41], v[40:41], v[192:193] op_sel_hi:[1,0]
	v_pk_mul_f32 v[38:39], v[38:39], v[192:193] op_sel_hi:[1,0]
	v_pk_mul_f32 v[36:37], v[36:37], v[192:193] op_sel_hi:[1,0]
	v_pk_mul_f32 v[34:35], v[34:35], v[192:193] op_sel_hi:[1,0]
	v_pk_mul_f32 v[32:33], v[32:33], v[192:193] op_sel_hi:[1,0]
	v_pk_mul_f32 v[30:31], v[30:31], v[192:193] op_sel_hi:[1,0]
	v_pk_mul_f32 v[28:29], v[28:29], v[192:193] op_sel_hi:[1,0]
	v_pk_mul_f32 v[26:27], v[26:27], v[192:193] op_sel_hi:[1,0]
	v_pk_mul_f32 v[24:25], v[24:25], v[192:193] op_sel_hi:[1,0]
	v_pk_mul_f32 v[22:23], v[22:23], v[192:193] op_sel_hi:[1,0]
	v_pk_mul_f32 v[20:21], v[20:21], v[192:193] op_sel_hi:[1,0]
	v_pk_mul_f32 v[18:19], v[18:19], v[192:193] op_sel_hi:[1,0]
	v_pk_mul_f32 v[16:17], v[16:17], v[192:193] op_sel_hi:[1,0]
	v_pk_mul_f32 v[14:15], v[14:15], v[192:193] op_sel_hi:[1,0]
	v_pk_mul_f32 v[12:13], v[12:13], v[192:193] op_sel_hi:[1,0]
	v_pk_mul_f32 v[10:11], v[10:11], v[192:193] op_sel_hi:[1,0]
	v_pk_mul_f32 v[8:9], v[8:9], v[192:193] op_sel_hi:[1,0]
	v_pk_mul_f32 v[6:7], v[6:7], v[192:193] op_sel_hi:[1,0]
	v_pk_mul_f32 v[4:5], v[4:5], v[192:193] op_sel_hi:[1,0]
	v_pk_mul_f32 v[2:3], v[2:3], v[192:193] op_sel_hi:[1,0]
	v_pk_mul_f32 v[0:1], v[0:1], v[192:193] op_sel_hi:[1,0]
	v_mul_f32_e32 v180, v180, v192
	v_add_f32_e32 v80, v80, v244
	v_add_f32_e32 v81, v81, v244
	v_add_f32_e32 v82, v82, v244
	v_add_f32_e32 v83, v83, v244
	v_add_f32_e32 v84, v84, v244
	v_add_f32_e32 v85, v85, v244
	v_add_f32_e32 v86, v86, v244
	v_add_f32_e32 v87, v87, v244
	v_add_f32_e32 v88, v88, v244
	v_add_f32_e32 v89, v89, v244
	v_add_f32_e32 v90, v90, v244
	v_add_f32_e32 v91, v91, v244
	v_add_f32_e32 v92, v92, v244
	v_add_f32_e32 v93, v93, v244
	v_add_f32_e32 v94, v94, v244
	v_add_f32_e32 v95, v95, v244
	v_add_f32_e32 v64, v64, v244
	v_add_f32_e32 v65, v65, v244
	v_add_f32_e32 v66, v66, v244
	v_add_f32_e32 v67, v67, v244
	v_add_f32_e32 v68, v68, v244
	v_add_f32_e32 v69, v69, v244
	v_add_f32_e32 v70, v70, v244
	v_add_f32_e32 v71, v71, v244
	v_add_f32_e32 v72, v72, v244
	v_add_f32_e32 v73, v73, v244
	v_add_f32_e32 v74, v74, v244
	v_add_f32_e32 v75, v75, v244
	v_add_f32_e32 v76, v76, v244
	v_add_f32_e32 v77, v77, v244
	v_add_f32_e32 v78, v78, v244
	v_add_f32_e32 v79, v79, v244
	v_sub_f32_e32 v226, 0, v193
	v_mov_b32_e32 v227, v226
	v_mov_b32_e32 v228, v226
	v_mov_b32_e32 v229, v226
	v_mov_b32_e32 v230, v226
	v_mov_b32_e32 v231, v226
	v_mov_b32_e32 v232, v226
	v_mov_b32_e32 v233, v226
	v_mov_b32_e32 v234, v226
	v_mov_b32_e32 v235, v226
	v_mov_b32_e32 v236, v226
	v_mov_b32_e32 v237, v226
	v_mov_b32_e32 v238, v226
	v_mov_b32_e32 v239, v226
	v_mov_b32_e32 v240, v226
	v_mov_b32_e32 v241, v226
; #define LAS __attribute__((address_space(3)))
; __device__ __forceinline__ void attn_unit(LAS unsigned char* lds, const bf16_t* Qg, const bf16_t* Kg, const bf16_t* Vtg, bf16_t* Og, int bh, int qb, int tid_, int wave, int lane_) {
;     ...
;         if (relc >= 0) {
;             const int thr = (relc == 0) ? r : -1;
; #pragma unroll
;     ...
;         float ps = 0.f; u32x4 p0, p1;
; #pragma unroll
;         for (int q = 0; q < 4; ++q) sn = MFMA32(fb[q], qf[4 + q], sn);
; #pragma unroll
;         for (int i = 0; i < 8; ++i) { sc[i] = __builtin_amdgcn_exp2f(sc[i] - mrun); ps += sc[i]; }
;         p0.x = pk2(sc[0], sc[1]); p0.y = pk2(sc[2], sc[3]); p0.z = pk2(sc[4], sc[5]); p0.w = pk2(sc[6], sc[7]);
;         __builtin_amdgcn_sched_barrier(0);
; #pragma unroll
;         for (int dt = 0; dt < 4; ++dt) fb[dt] = *(const LAS bf16x8*)(vb + vro[0] + dt * 4096);
;         __builtin_amdgcn_sched_barrier(0);
;         ATT_ISSUE_K(j3, s0);
;         __builtin_amdgcn_sched_barrier(0);
; #pragma unroll
;         for (int q = 0; q < 4; ++q) sn = MFMA32(fa[q], qf[8 + q], sn);
; #pragma unroll
;         for (int i = 8; i < 12; ++i) { sc[i] = __builtin_amdgcn_exp2f(sc[i] - mrun); ps += sc[i]; }
;         p1.x = pk2(sc[8], sc[9]); p1.y = pk2(sc[10], sc[11]);
;         __builtin_amdgcn_sched_barrier(0);
;         ATT_ISSUE_V(j2, s2);
;         __builtin_amdgcn_sched_barrier(0);
; #pragma unroll
;         for (int dt = 0; dt < 4; ++dt) fa[dt] = *(const LAS bf16x8*)(vb + vro[1] + dt * 4096);
;         { const bf16x8 pf0 = __builtin_bit_cast(bf16x8, p0);
;           o[0] = MFMA32(fb[0], pf0, o[0]); o[1] = MFMA32(fb[1], pf0, o[1]); o[2] = MFMA32(fb[2], pf0, o[2]); o[3] = MFMA32(fb[3], pf0, o[3]); }
; #pragma unroll
;         for (int i = 12; i < 16; ++i) { sc[i] = __builtin_amdgcn_exp2f(sc[i] - mrun); ps += sc[i]; }
;         p1.z = pk2(sc[12], sc[13]); p1.w = pk2(sc[14], sc[15]);
;         lrun += ps;
;         __builtin_amdgcn_sched_barrier(0);
;         { const bf16x8 pf1 = __builtin_bit_cast(bf16x8, p1);
;           o[0] = MFMA32(fa[0], pf1, o[0]); o[1] = MFMA32(fa[1], pf1, o[1]); o[2] = MFMA32(fa[2], pf1, o[2]); o[3] = MFMA32(fa[3], pf1, o[3]); }
;         asm volatile("s_waitcnt vmcnt(5) lgkmcnt(0)" ::: "memory"); __builtin_amdgcn_s_barrier(); asm volatile("" ::: "memory");
;         sc = sn;
;         { const int t = s0; s0 = s1; s1 = s2; s2 = t; }
;     }
.Lattb_u2_492:
	v_mfma_f32_32x32x16_bf16 v[64:79], v[164:167], v[112:115], v[64:79]
	v_exp_f32_e32 v192, v80
	v_exp_f32_e32 v193, v81
	v_exp_f32_e32 v194, v82
	s_waitcnt lgkmcnt(0)
	v_mfma_f32_32x32x16_bf16 v[64:79], v[172:175], v[116:119], v[64:79]
	v_exp_f32_e32 v207, v83
	v_exp_f32_e32 v208, v84
	v_exp_f32_e32 v209, v85
	v_exp_f32_e32 v210, v86
	v_mfma_f32_32x32x16_bf16 v[64:79], v[168:171], v[120:123], v[64:79]
	s_add_i32 s0, s57, 3
	v_exp_f32_e32 v211, v87
	s_cmp_lt_i32 s0, s45
	s_cselect_b32 s0, s0, s44
	s_add_i32 s1, s57, 2
	s_cmp_lt_i32 s57, s52
	s_cselect_b32 s48, s1, s44
	v_cvt_pk_bf16_f32 v246, v192, v193
	v_cvt_pk_bf16_f32 v247, v194, v207
	v_cvt_pk_bf16_f32 v248, v208, v209
	v_cvt_pk_bf16_f32 v249, v210, v211
	ds_read_b128 v[214:217], v225 offset:32768
	ds_read_b128 v[164:167], v225 offset:36864
	ds_read_b128 v[168:171], v225 offset:40960
	ds_read_b128 v[172:175], v225 offset:45056
	v_add_f32_e32 v192, v193, v192
	v_add_f32_e32 v192, v194, v192
	v_add_f32_e32 v192, v207, v192
	v_add_f32_e32 v192, v208, v192
	v_add_f32_e32 v192, v209, v192
	v_add_f32_e32 v192, v210, v192
	v_add_f32_e32 v194, v211, v192
	s_mul_hi_u32 s1, s0, 0x6000
	s_mulk_i32 s0, 0x6000
	s_add_u32 s0, s92, s0
	s_mul_i32 s12, s58, 0x6000
	s_addc_u32 s1, s93, s1
	s_add_i32 s12, s71, s12
	s_mov_b32 m0, s12
	s_waitcnt lgkmcnt(5)
	v_mfma_f32_32x32x16_bf16 v[64:79], v[160:163], v[124:127], v[64:79]
	global_load_lds_dwordx4 v182, s[0:1]
	s_add_i32 m0, s12, 0x400
	s_nop 0
	global_load_lds_dwordx4 v184, s[0:1]
	s_add_i32 m0, s12, 0x800
	s_nop 0
	global_load_lds_dwordx4 v186, s[0:1]
	v_mfma_f32_32x32x16_bf16 v[64:79], v[148:151], v[128:131], v[64:79]
	v_exp_f32_e32 v220, v88
	v_exp_f32_e32 v221, v89
	v_exp_f32_e32 v222, v90
	v_mfma_f32_32x32x16_bf16 v[64:79], v[156:159], v[132:135], v[64:79]
	v_exp_f32_e32 v223, v91
	v_add_f32_e32 v148, v220, v194
	v_add_f32_e32 v148, v221, v148
	v_add_f32_e32 v148, v222, v148
	v_add_f32_e32 v156, v223, v148
	v_cvt_pk_bf16_f32 v250, v220, v221
	v_cvt_pk_bf16_f32 v251, v222, v223
	v_mfma_f32_32x32x16_bf16 v[64:79], v[152:155], v[136:139], v[64:79]
	v_exp_f32_e32 v220, v92
	v_exp_f32_e32 v221, v93
	v_exp_f32_e32 v222, v94
	v_exp_f32_e32 v223, v95
	s_waitcnt lgkmcnt(0)
	v_mfma_f32_32x32x16_bf16 v[80:95], v[144:147], v[140:143], v[64:79]
	s_lshl_b64 s[0:1], s[48:49], 7
	s_add_u32 s0, s94, s0
	s_addc_u32 s1, s95, s1
	s_lshl_b32 s12, s53, 14
	s_add_i32 s12, s12, 0
	s_add_i32 s12, s12, s68
	s_add_i32 m0, s12, 0x12000
	s_nop 0
	global_load_lds_dwordx4 v176, s[0:1]
	s_add_i32 m0, s12, 0x12400
	s_nop 0
	global_load_lds_dwordx4 v188, s[0:1]
	v_mfma_f32_32x32x16_bf16 v[48:63], v[214:217], v[246:249], v[48:63]
	ds_read_b128 v[214:217], v245 offset:32768
	ds_read_b128 v[144:147], v245 offset:36864
	ds_read_b128 v[148:151], v245 offset:40960
	ds_read_b128 v[152:155], v245 offset:45056
	v_mfma_f32_32x32x16_bf16 v[32:47], v[164:167], v[246:249], v[32:47]
	v_add_f32_e32 v213, v220, v156
	v_add_f32_e32 v213, v221, v213
	v_add_f32_e32 v213, v222, v213
	v_add_f32_e32 v213, v223, v213
	v_add_f32_e32 v180, v180, v213
	v_mfma_f32_32x32x16_bf16 v[16:31], v[168:171], v[246:249], v[16:31]
	v_cvt_pk_bf16_f32 v252, v220, v221
	v_cvt_pk_bf16_f32 v253, v222, v223
	v_mfma_f32_32x32x16_bf16 v[0:15], v[172:175], v[246:249], v[0:15]
	s_waitcnt lgkmcnt(0)
	v_mfma_f32_32x32x16_bf16 v[48:63], v[214:217], v[250:253], v[48:63]
	s_waitcnt vmcnt(5) lgkmcnt(0)
	s_barrier
	s_add_i32 s57, s57, 1
	s_add_i32 s56, s56, 64
	s_cmp_eq_u32 s45, s57
	v_mfma_f32_32x32x16_bf16 v[32:47], v[144:147], v[250:253], v[32:47]
	v_mfma_f32_32x32x16_bf16 v[16:31], v[148:151], v[250:253], v[16:31]
	v_mfma_f32_32x32x16_bf16 v[0:15], v[152:155], v[250:253], v[0:15]
	s_cbranch_scc1 .LBB0_495
	s_mov_b32 s0, s55
	s_mov_b32 s55, s53
	s_mov_b32 s53, s58
	s_add_i32 s1, s54, s56
	s_cmp_lt_i32 s1, 0
	s_mov_b32 s58, s0
	s_cbranch_scc0 .LBB0_488
	s_branch .LBB0_489
.LBB0_488:
	s_cmp_eq_u32 s1, 0
	s_cselect_b64 vcc, -1, 0
	v_cndmask_b32_e32 v213, -1, v191, vcc
	v_sub_u32_e32 v213, v213, v205
	v_cmp_gt_i32_e64 s[38:39], 26, v213
	v_cmp_gt_i32_e64 s[40:41], 27, v213
	v_cmp_gt_i32_e64 s[36:37], 25, v213
	s_and_b64 s[38:39], s[40:41], s[38:39]
	v_cmp_gt_i32_e64 s[34:35], 24, v213
	s_and_b64 s[36:37], s[38:39], s[36:37]
	v_cmp_gt_i32_e64 s[30:31], 19, v213
	s_and_b64 s[34:35], s[36:37], s[34:35]
	v_cmp_gt_i32_e64 s[28:29], 18, v213
	s_and_b64 s[30:31], s[34:35], s[30:31]
	v_cmp_gt_i32_e64 s[26:27], 17, v213
	s_and_b64 s[28:29], s[30:31], s[28:29]
	v_cmp_gt_i32_e64 s[24:25], 16, v213
	s_and_b64 s[26:27], s[28:29], s[26:27]
	v_cmp_gt_i32_e64 s[22:23], 11, v213
	s_and_b64 s[24:25], s[26:27], s[24:25]
	v_cmp_gt_i32_e64 s[20:21], 10, v213
	s_and_b64 s[22:23], s[24:25], s[22:23]
	v_cmp_gt_i32_e64 s[18:19], 9, v213
	s_and_b64 s[20:21], s[22:23], s[20:21]
	v_cmp_gt_i32_e64 s[16:17], 8, v213
	s_and_b64 s[18:19], s[20:21], s[18:19]
	v_cmp_gt_i32_e64 s[14:15], 3, v213
	s_and_b64 s[16:17], s[18:19], s[16:17]
	v_cmp_gt_i32_e64 s[12:13], 2, v213
	s_and_b64 s[14:15], s[16:17], s[14:15]
	v_cmp_gt_i32_e64 s[0:1], 1, v213
	s_and_b64 s[12:13], s[14:15], s[12:13]
	v_cmp_gt_i32_e32 vcc, 0, v213
	s_and_b64 s[0:1], s[12:13], s[0:1]
	s_and_b64 vcc, s[0:1], vcc
	v_cndmask_b32_e64 v95, v95, v196, s[40:41]
	v_cndmask_b32_e64 v94, v94, v196, s[38:39]
	v_cndmask_b32_e64 v93, v93, v196, s[36:37]
	v_cndmask_b32_e64 v92, v92, v196, s[34:35]
	v_cndmask_b32_e64 v91, v91, v196, s[30:31]
	v_cndmask_b32_e64 v90, v90, v196, s[28:29]
	v_cndmask_b32_e64 v89, v89, v196, s[26:27]
	v_cndmask_b32_e64 v88, v88, v196, s[24:25]
	v_cndmask_b32_e64 v87, v87, v196, s[22:23]
	v_cndmask_b32_e64 v86, v86, v196, s[20:21]
	v_cndmask_b32_e64 v85, v85, v196, s[18:19]
	v_cndmask_b32_e64 v84, v84, v196, s[16:17]
	v_cndmask_b32_e64 v83, v83, v196, s[14:15]
	v_cndmask_b32_e64 v82, v82, v196, s[12:13]
	v_cndmask_b32_e64 v81, v81, v196, s[0:1]
	v_cndmask_b32_e32 v80, v80, v196, vcc
	s_branch .LBB0_490
; __device__ __forceinline__ unsigned pk2(float a, float b) { f32x2_t v = {a, b}; bf16x2v_t r = __builtin_convertvector(v, bf16x2v_t); return __builtin_bit_cast(unsigned, r); }
; #define LAS __attribute__((address_space(3)))
; __device__ __forceinline__ void attn_unit(LAS unsigned char* lds, const bf16_t* Qg, const bf16_t* Kg, const bf16_t* Vtg, bf16_t* Og, int bh, int qb, int tid_, int wave, int lane_) {
;     ...
;         if (relc >= 0) {
;             const int thr = (relc == 0) ? r : -1;
; #pragma unroll
;             for (int i = 0; i < 16; ++i) { const int key = (i & 3) + 8 * (i >> 2) + 4 * hi; if (key > thr) sc[i] = NINF; }
;         }
;     ...
;     asm volatile("s_waitcnt vmcnt(0) lgkmcnt(0)" ::: "memory"); __builtin_amdgcn_s_barrier(); asm volatile("" ::: "memory");
;     LAS float* cs = (LAS float*)(lds + rg * (66 * 64 * 4)) + lane;
;     if (kh == 1) {
; #pragma unroll
;         for (int dt = 0; dt < 4; ++dt)
; #pragma unroll
;             for (int i = 0; i < 16; ++i) cs[(dt * 16 + i) * 64] = o[dt][i];
;         cs[64 * 64] = mrun; cs[65 * 64] = lrun;
;     }
;     __syncthreads();
;     if (kh == 0) {
;         const float m1 = cs[64 * 64], l1 = cs[65 * 64];
;         const float mf = fmaxf(mrun, m1), a0 = __builtin_amdgcn_exp2f(mrun - mf), a1 = __builtin_amdgcn_exp2f(m1 - mf);
;         float lt = lrun * a0 + l1 * a1; lt += __shfl_xor(lt, 32);
;         const float inv = 1.f / lt;
;         bf16_t* op = Og + ((size_t)b * SEQ + 128 * qb + 32 * rg + r) * AW + h * VD + 4 * hi;
; #pragma unroll
;         for (int dt = 0; dt < 4; ++dt)
; #pragma unroll
;             for (int g = 0; g < 4; ++g) {
;                 float v[4];
; #pragma unroll
;                 for (int e = 0; e < 4; ++e) v[e] = (o[dt][4 * g + e] * a0 + cs[(dt * 16 + 4 * g + e) * 64] * a1) * inv;
;                 u32x2 w; w.x = pk2(v[0], v[1]); w.y = pk2(v[2], v[3]);
;                 *(u32x2*)(op + 32 * dt + 8 * g) = w;
.Lattb_u1_488:
	s_cmp_eq_u32 s1, 0
	s_cselect_b64 vcc, -1, 0
	v_cndmask_b32_e32 v213, -1, v191, vcc
	v_sub_u32_e32 v213, v213, v205
	v_cmp_gt_i32_e64 s[38:39], 26, v213
	v_cmp_gt_i32_e64 s[40:41], 27, v213
	v_cmp_gt_i32_e64 s[36:37], 25, v213
	s_and_b64 s[38:39], s[40:41], s[38:39]
	v_cmp_gt_i32_e64 s[34:35], 24, v213
	s_and_b64 s[36:37], s[38:39], s[36:37]
	v_cmp_gt_i32_e64 s[30:31], 19, v213
	s_and_b64 s[34:35], s[36:37], s[34:35]
	v_cmp_gt_i32_e64 s[28:29], 18, v213
	s_and_b64 s[30:31], s[34:35], s[30:31]
	v_cmp_gt_i32_e64 s[26:27], 17, v213
	s_and_b64 s[28:29], s[30:31], s[28:29]
	v_cmp_gt_i32_e64 s[24:25], 16, v213
	s_and_b64 s[26:27], s[28:29], s[26:27]
	v_cmp_gt_i32_e64 s[22:23], 11, v213
	s_and_b64 s[24:25], s[26:27], s[24:25]
	v_cmp_gt_i32_e64 s[20:21], 10, v213
	s_and_b64 s[22:23], s[24:25], s[22:23]
	v_cmp_gt_i32_e64 s[18:19], 9, v213
	s_and_b64 s[20:21], s[22:23], s[20:21]
	v_cmp_gt_i32_e64 s[16:17], 8, v213
	s_and_b64 s[18:19], s[20:21], s[18:19]
	v_cmp_gt_i32_e64 s[14:15], 3, v213
	s_and_b64 s[16:17], s[18:19], s[16:17]
	v_cmp_gt_i32_e64 s[12:13], 2, v213
	s_and_b64 s[14:15], s[16:17], s[14:15]
	v_cmp_gt_i32_e64 s[0:1], 1, v213
	s_and_b64 s[12:13], s[14:15], s[12:13]
	v_cmp_gt_i32_e32 vcc, 0, v213
	s_and_b64 s[0:1], s[12:13], s[0:1]
	s_and_b64 vcc, s[0:1], vcc
	v_cndmask_b32_e64 v95, v95, v196, s[40:41]
	v_cndmask_b32_e64 v94, v94, v196, s[38:39]
	v_cndmask_b32_e64 v93, v93, v196, s[36:37]
	v_cndmask_b32_e64 v92, v92, v196, s[34:35]
	v_cndmask_b32_e64 v91, v91, v196, s[30:31]
	v_cndmask_b32_e64 v90, v90, v196, s[28:29]
	v_cndmask_b32_e64 v89, v89, v196, s[26:27]
	v_cndmask_b32_e64 v88, v88, v196, s[24:25]
	v_cndmask_b32_e64 v87, v87, v196, s[22:23]
	v_cndmask_b32_e64 v86, v86, v196, s[20:21]
	v_cndmask_b32_e64 v85, v85, v196, s[18:19]
	v_cndmask_b32_e64 v84, v84, v196, s[16:17]
	v_cndmask_b32_e64 v83, v83, v196, s[14:15]
	v_cndmask_b32_e64 v82, v82, v196, s[12:13]
	v_cndmask_b32_e64 v81, v81, v196, s[0:1]
	v_cndmask_b32_e32 v80, v80, v196, vcc
	s_branch .Lattb_u1_490
.Lattb_u2_488:
	s_cmp_eq_u32 s1, 0
	s_cselect_b64 vcc, -1, 0
	v_cndmask_b32_e32 v213, -1, v191, vcc
	v_sub_u32_e32 v213, v213, v205
	v_cmp_gt_i32_e64 s[38:39], 26, v213
	v_cmp_gt_i32_e64 s[40:41], 27, v213
	v_cmp_gt_i32_e64 s[36:37], 25, v213
	s_and_b64 s[38:39], s[40:41], s[38:39]
	v_cmp_gt_i32_e64 s[34:35], 24, v213
	s_and_b64 s[36:37], s[38:39], s[36:37]
	v_cmp_gt_i32_e64 s[30:31], 19, v213
	s_and_b64 s[34:35], s[36:37], s[34:35]
	v_cmp_gt_i32_e64 s[28:29], 18, v213
	s_and_b64 s[30:31], s[34:35], s[30:31]
	v_cmp_gt_i32_e64 s[26:27], 17, v213
	s_and_b64 s[28:29], s[30:31], s[28:29]
	v_cmp_gt_i32_e64 s[24:25], 16, v213
	s_and_b64 s[26:27], s[28:29], s[26:27]
	v_cmp_gt_i32_e64 s[22:23], 11, v213
	s_and_b64 s[24:25], s[26:27], s[24:25]
	v_cmp_gt_i32_e64 s[20:21], 10, v213
	s_and_b64 s[22:23], s[24:25], s[22:23]
	v_cmp_gt_i32_e64 s[18:19], 9, v213
	s_and_b64 s[20:21], s[22:23], s[20:21]
	v_cmp_gt_i32_e64 s[16:17], 8, v213
	s_and_b64 s[18:19], s[20:21], s[18:19]
	v_cmp_gt_i32_e64 s[14:15], 3, v213
	s_and_b64 s[16:17], s[18:19], s[16:17]
	v_cmp_gt_i32_e64 s[12:13], 2, v213
	s_and_b64 s[14:15], s[16:17], s[14:15]
	v_cmp_gt_i32_e64 s[0:1], 1, v213
	s_and_b64 s[12:13], s[14:15], s[12:13]
	v_cmp_gt_i32_e32 vcc, 0, v213
	s_and_b64 s[0:1], s[12:13], s[0:1]
	s_and_b64 vcc, s[0:1], vcc
	v_cndmask_b32_e64 v95, v95, v196, s[40:41]
	v_cndmask_b32_e64 v94, v94, v196, s[38:39]
	v_cndmask_b32_e64 v93, v93, v196, s[36:37]
	v_cndmask_b32_e64 v92, v92, v196, s[34:35]
	v_cndmask_b32_e64 v91, v91, v196, s[30:31]
	v_cndmask_b32_e64 v90, v90, v196, s[28:29]
	v_cndmask_b32_e64 v89, v89, v196, s[26:27]
	v_cndmask_b32_e64 v88, v88, v196, s[24:25]
	v_cndmask_b32_e64 v87, v87, v196, s[22:23]
	v_cndmask_b32_e64 v86, v86, v196, s[20:21]
	v_cndmask_b32_e64 v85, v85, v196, s[18:19]
	v_cndmask_b32_e64 v84, v84, v196, s[16:17]
	v_cndmask_b32_e64 v83, v83, v196, s[14:15]
	v_cndmask_b32_e64 v82, v82, v196, s[12:13]
	v_cndmask_b32_e64 v81, v81, v196, s[0:1]
	v_cndmask_b32_e32 v80, v80, v196, vcc
	s_branch .Lattb_u2_490
.LBB0_494:
	v_mov_b32_e32 v198, 0xf149f2ca
	v_mov_b32_e32 v63, 0
	v_mov_b32_e32 v62, 0
	v_mov_b32_e32 v61, 0
	v_mov_b32_e32 v60, 0
	v_mov_b32_e32 v59, 0
	v_mov_b32_e32 v58, 0
	v_mov_b32_e32 v57, 0
	v_mov_b32_e32 v56, 0
	v_mov_b32_e32 v55, 0
	v_mov_b32_e32 v54, 0
	v_mov_b32_e32 v53, 0
	v_mov_b32_e32 v52, 0
	v_mov_b32_e32 v51, 0
	v_mov_b32_e32 v50, 0
	v_mov_b32_e32 v49, 0
	v_mov_b32_e32 v48, 0
	v_mov_b32_e32 v47, 0
	v_mov_b32_e32 v46, 0
	v_mov_b32_e32 v45, 0
	v_mov_b32_e32 v44, 0
	v_mov_b32_e32 v43, 0
	v_mov_b32_e32 v42, 0
	v_mov_b32_e32 v41, 0
	v_mov_b32_e32 v40, 0
	v_mov_b32_e32 v39, 0
	v_mov_b32_e32 v38, 0
	v_mov_b32_e32 v37, 0
	v_mov_b32_e32 v36, 0
	v_mov_b32_e32 v35, 0
	v_mov_b32_e32 v34, 0
	v_mov_b32_e32 v33, 0
	v_mov_b32_e32 v32, 0
	v_mov_b32_e32 v31, 0
	v_mov_b32_e32 v30, 0
	v_mov_b32_e32 v29, 0
	v_mov_b32_e32 v28, 0
	v_mov_b32_e32 v27, 0
	v_mov_b32_e32 v26, 0
	v_mov_b32_e32 v25, 0
	v_mov_b32_e32 v24, 0
	v_mov_b32_e32 v23, 0
	v_mov_b32_e32 v22, 0
	v_mov_b32_e32 v21, 0
	v_mov_b32_e32 v20, 0
	v_mov_b32_e32 v19, 0
	v_mov_b32_e32 v18, 0
	v_mov_b32_e32 v17, 0
	v_mov_b32_e32 v16, 0
	v_mov_b32_e32 v15, 0
	v_mov_b32_e32 v14, 0
	v_mov_b32_e32 v13, 0
	v_mov_b32_e32 v12, 0
	v_mov_b32_e32 v11, 0
	v_mov_b32_e32 v10, 0
	v_mov_b32_e32 v9, 0
	v_mov_b32_e32 v8, 0
	v_mov_b32_e32 v7, 0
	v_mov_b32_e32 v6, 0
	v_mov_b32_e32 v5, 0
	v_mov_b32_e32 v4, 0
	v_mov_b32_e32 v3, 0
	v_mov_b32_e32 v2, 0
	v_mov_b32_e32 v1, 0
	v_mov_b32_e32 v0, 0
	v_mov_b32_e32 v180, 0
	s_mov_b64 s[88:89], s[8:9]
